# v21 + spec_mul blocks software pipelined (next 2 elements' LDS reads issued before the current 2 are computed)
# speedup vs baseline: 1.0123x; 1.0123x over previous
.LBB0_433:
	v_add_u32_e32 v160, 0x11000, v155
	v_lshlrev_b32_e32 v161, 3, v154
	v_add_u32_e32 v161, 0x2200, v161
	v_add_u32_e32 v162, 0x11100, v156
	v_cmp_ne_u32_e32 vcc, 0, v32
	v_cndmask_b32_e32 v163, 0, v154, vcc
	v_lshlrev_b32_e32 v163, 3, v163
	v_add_u32_e32 v163, 0x11000, v163
	ds_read_b64 v[214:215], v160 offset:0
	ds_read_b64 v[216:217], v163
	ds_read_b64 v[218:219], v155 offset:0
	ds_read_b64 v[220:221], v160 offset:4352
	ds_read_b64 v[222:223], v162 offset:60928
	ds_read_b64 v[224:225], v155 offset:4352
	ds_read_b64 v[226:227], v160 offset:8704
	ds_read_b64 v[228:229], v161 offset:52224
	ds_read_b64 v[230:231], v155 offset:8704
	ds_read_b64 v[232:233], v160 offset:13056
	ds_read_b64 v[234:235], v162 offset:52224
	ds_read_b64 v[236:237], v155 offset:13056
	s_waitcnt lgkmcnt(9)
	v_add_f32_e32 v164, v214, v216
	v_mul_f32_e32 v214, 0.5, v164
	v_sub_f32_e32 v164, v215, v217
	v_mul_f32_e32 v216, 0.5, v164
	v_pk_mul_f32 v[216:217], v[218:219], v[216:217] op_sel:[1,0] op_sel_hi:[0,0]
	v_pk_fma_f32 v[158:159], v[218:219], v[214:215], v[216:217] neg_lo:[0,0,1] neg_hi:[0,0,1]
	v_pk_fma_f32 v[214:215], v[218:219], v[214:215], v[216:217] op_sel_hi:[1,0,1]
	s_nop 0
	v_mov_b32_e32 v159, v215
	v_pk_mul_f32 v[218:219], v[158:159], s[24:25]
	ds_write_b64 v155, v[218:219] offset:0
	s_waitcnt lgkmcnt(7)
	v_add_f32_e32 v164, v220, v222
	v_mul_f32_e32 v220, 0.5, v164
	v_sub_f32_e32 v164, v221, v223
	v_mul_f32_e32 v222, 0.5, v164
	v_pk_mul_f32 v[222:223], v[224:225], v[222:223] op_sel:[1,0] op_sel_hi:[0,0]
	v_pk_fma_f32 v[158:159], v[224:225], v[220:221], v[222:223] neg_lo:[0,0,1] neg_hi:[0,0,1]
	v_pk_fma_f32 v[220:221], v[224:225], v[220:221], v[222:223] op_sel_hi:[1,0,1]
	s_nop 0
	v_mov_b32_e32 v159, v221
	v_pk_mul_f32 v[224:225], v[158:159], s[24:25]
	ds_write_b64 v155, v[224:225] offset:4352
	ds_read_b64 v[182:183], v160 offset:17408
	ds_read_b64 v[184:185], v161 offset:43520
	ds_read_b64 v[186:187], v155 offset:17408
	ds_read_b64 v[188:189], v160 offset:21760
	ds_read_b64 v[190:191], v162 offset:43520
	ds_read_b64 v[192:193], v155 offset:21760
	s_waitcnt lgkmcnt(11)
	v_add_f32_e32 v164, v226, v228
	v_mul_f32_e32 v226, 0.5, v164
	v_sub_f32_e32 v164, v227, v229
	v_mul_f32_e32 v228, 0.5, v164
	v_pk_mul_f32 v[228:229], v[230:231], v[228:229] op_sel:[1,0] op_sel_hi:[0,0]
	v_pk_fma_f32 v[158:159], v[230:231], v[226:227], v[228:229] neg_lo:[0,0,1] neg_hi:[0,0,1]
	v_pk_fma_f32 v[226:227], v[230:231], v[226:227], v[228:229] op_sel_hi:[1,0,1]
	s_nop 0
	v_mov_b32_e32 v159, v227
	v_pk_mul_f32 v[230:231], v[158:159], s[24:25]
	ds_write_b64 v155, v[230:231] offset:8704
	s_waitcnt lgkmcnt(9)
	v_add_f32_e32 v164, v232, v234
	v_mul_f32_e32 v232, 0.5, v164
	v_sub_f32_e32 v164, v233, v235
	v_mul_f32_e32 v234, 0.5, v164
	v_pk_mul_f32 v[234:235], v[236:237], v[234:235] op_sel:[1,0] op_sel_hi:[0,0]
	v_pk_fma_f32 v[158:159], v[236:237], v[232:233], v[234:235] neg_lo:[0,0,1] neg_hi:[0,0,1]
	v_pk_fma_f32 v[232:233], v[236:237], v[232:233], v[234:235] op_sel_hi:[1,0,1]
	s_nop 0
	v_mov_b32_e32 v159, v233
	v_pk_mul_f32 v[236:237], v[158:159], s[24:25]
	ds_write_b64 v155, v[236:237] offset:13056
	ds_read_b64 v[214:215], v160 offset:26112
	ds_read_b64 v[216:217], v161 offset:34816
	ds_read_b64 v[218:219], v155 offset:26112
	ds_read_b64 v[220:221], v160 offset:30464
	ds_read_b64 v[222:223], v162 offset:34816
	ds_read_b64 v[224:225], v155 offset:30464
	s_waitcnt lgkmcnt(11)
	v_add_f32_e32 v164, v182, v184
	v_mul_f32_e32 v182, 0.5, v164
	v_sub_f32_e32 v164, v183, v185
	v_mul_f32_e32 v184, 0.5, v164
	v_pk_mul_f32 v[184:185], v[186:187], v[184:185] op_sel:[1,0] op_sel_hi:[0,0]
	v_pk_fma_f32 v[158:159], v[186:187], v[182:183], v[184:185] neg_lo:[0,0,1] neg_hi:[0,0,1]
	v_pk_fma_f32 v[182:183], v[186:187], v[182:183], v[184:185] op_sel_hi:[1,0,1]
	s_nop 0
	v_mov_b32_e32 v159, v183
	v_pk_mul_f32 v[186:187], v[158:159], s[24:25]
	ds_write_b64 v155, v[186:187] offset:17408
	s_waitcnt lgkmcnt(9)
	v_add_f32_e32 v164, v188, v190
	v_mul_f32_e32 v188, 0.5, v164
	v_sub_f32_e32 v164, v189, v191
	v_mul_f32_e32 v190, 0.5, v164
	v_pk_mul_f32 v[190:191], v[192:193], v[190:191] op_sel:[1,0] op_sel_hi:[0,0]
	v_pk_fma_f32 v[158:159], v[192:193], v[188:189], v[190:191] neg_lo:[0,0,1] neg_hi:[0,0,1]
	v_pk_fma_f32 v[188:189], v[192:193], v[188:189], v[190:191] op_sel_hi:[1,0,1]
	s_nop 0
	v_mov_b32_e32 v159, v189
	v_pk_mul_f32 v[192:193], v[158:159], s[24:25]
	ds_write_b64 v155, v[192:193] offset:21760
	ds_read_b64 v[226:227], v160 offset:34816
	ds_read_b64 v[228:229], v161 offset:26112
	ds_read_b64 v[230:231], v155 offset:34816
	ds_read_b64 v[232:233], v160 offset:39168
	ds_read_b64 v[234:235], v162 offset:26112
	ds_read_b64 v[236:237], v155 offset:39168
	s_waitcnt lgkmcnt(11)
	v_add_f32_e32 v164, v214, v216
	v_mul_f32_e32 v214, 0.5, v164
	v_sub_f32_e32 v164, v215, v217
	v_mul_f32_e32 v216, 0.5, v164
	v_pk_mul_f32 v[216:217], v[218:219], v[216:217] op_sel:[1,0] op_sel_hi:[0,0]
	v_pk_fma_f32 v[158:159], v[218:219], v[214:215], v[216:217] neg_lo:[0,0,1] neg_hi:[0,0,1]
	v_pk_fma_f32 v[214:215], v[218:219], v[214:215], v[216:217] op_sel_hi:[1,0,1]
	s_nop 0
	v_mov_b32_e32 v159, v215
	v_pk_mul_f32 v[218:219], v[158:159], s[24:25]
	ds_write_b64 v155, v[218:219] offset:26112
	s_waitcnt lgkmcnt(9)
	v_add_f32_e32 v164, v220, v222
	v_mul_f32_e32 v220, 0.5, v164
	v_sub_f32_e32 v164, v221, v223
	v_mul_f32_e32 v222, 0.5, v164
	v_pk_mul_f32 v[222:223], v[224:225], v[222:223] op_sel:[1,0] op_sel_hi:[0,0]
	v_pk_fma_f32 v[158:159], v[224:225], v[220:221], v[222:223] neg_lo:[0,0,1] neg_hi:[0,0,1]
	v_pk_fma_f32 v[220:221], v[224:225], v[220:221], v[222:223] op_sel_hi:[1,0,1]
	s_nop 0
	v_mov_b32_e32 v159, v221
	v_pk_mul_f32 v[224:225], v[158:159], s[24:25]
	ds_write_b64 v155, v[224:225] offset:30464
	ds_read_b64 v[182:183], v160 offset:43520
	ds_read_b64 v[184:185], v161 offset:17408
	ds_read_b64 v[186:187], v155 offset:43520
	ds_read_b64 v[188:189], v160 offset:47872
	ds_read_b64 v[190:191], v162 offset:17408
	ds_read_b64 v[192:193], v155 offset:47872
	s_waitcnt lgkmcnt(11)
	v_add_f32_e32 v164, v226, v228
	v_mul_f32_e32 v226, 0.5, v164
	v_sub_f32_e32 v164, v227, v229
	v_mul_f32_e32 v228, 0.5, v164
	v_pk_mul_f32 v[228:229], v[230:231], v[228:229] op_sel:[1,0] op_sel_hi:[0,0]
	v_pk_fma_f32 v[158:159], v[230:231], v[226:227], v[228:229] neg_lo:[0,0,1] neg_hi:[0,0,1]
	v_pk_fma_f32 v[226:227], v[230:231], v[226:227], v[228:229] op_sel_hi:[1,0,1]
	s_nop 0
	v_mov_b32_e32 v159, v227
	v_pk_mul_f32 v[230:231], v[158:159], s[24:25]
	ds_write_b64 v155, v[230:231] offset:34816
	s_waitcnt lgkmcnt(9)
	v_add_f32_e32 v164, v232, v234
	v_mul_f32_e32 v232, 0.5, v164
	v_sub_f32_e32 v164, v233, v235
	v_mul_f32_e32 v234, 0.5, v164
	v_pk_mul_f32 v[234:235], v[236:237], v[234:235] op_sel:[1,0] op_sel_hi:[0,0]
	v_pk_fma_f32 v[158:159], v[236:237], v[232:233], v[234:235] neg_lo:[0,0,1] neg_hi:[0,0,1]
	v_pk_fma_f32 v[232:233], v[236:237], v[232:233], v[234:235] op_sel_hi:[1,0,1]
	s_nop 0
	v_mov_b32_e32 v159, v233
	v_pk_mul_f32 v[236:237], v[158:159], s[24:25]
	ds_write_b64 v155, v[236:237] offset:39168
	ds_read_b64 v[214:215], v160 offset:52224
	ds_read_b64 v[216:217], v161 offset:8704
	ds_read_b64 v[218:219], v155 offset:52224
	ds_read_b64 v[220:221], v160 offset:56576
	ds_read_b64 v[222:223], v162 offset:8704
	ds_read_b64 v[224:225], v155 offset:56576
	s_waitcnt lgkmcnt(11)
	v_add_f32_e32 v164, v182, v184
	v_mul_f32_e32 v182, 0.5, v164
	v_sub_f32_e32 v164, v183, v185
	v_mul_f32_e32 v184, 0.5, v164
	v_pk_mul_f32 v[184:185], v[186:187], v[184:185] op_sel:[1,0] op_sel_hi:[0,0]
	v_pk_fma_f32 v[158:159], v[186:187], v[182:183], v[184:185] neg_lo:[0,0,1] neg_hi:[0,0,1]
	v_pk_fma_f32 v[182:183], v[186:187], v[182:183], v[184:185] op_sel_hi:[1,0,1]
	s_nop 0
	v_mov_b32_e32 v159, v183
	v_pk_mul_f32 v[186:187], v[158:159], s[24:25]
	ds_write_b64 v155, v[186:187] offset:43520
	s_waitcnt lgkmcnt(9)
	v_add_f32_e32 v164, v188, v190
	v_mul_f32_e32 v188, 0.5, v164
	v_sub_f32_e32 v164, v189, v191
	v_mul_f32_e32 v190, 0.5, v164
	v_pk_mul_f32 v[190:191], v[192:193], v[190:191] op_sel:[1,0] op_sel_hi:[0,0]
	v_pk_fma_f32 v[158:159], v[192:193], v[188:189], v[190:191] neg_lo:[0,0,1] neg_hi:[0,0,1]
	v_pk_fma_f32 v[188:189], v[192:193], v[188:189], v[190:191] op_sel_hi:[1,0,1]
	s_nop 0
	v_mov_b32_e32 v159, v189
	v_pk_mul_f32 v[192:193], v[158:159], s[24:25]
	ds_write_b64 v155, v[192:193] offset:47872
	ds_read_b64 v[226:227], v160 offset:60928
	ds_read_b64 v[228:229], v161 offset:0
	ds_read_b64 v[230:231], v155 offset:60928
	ds_read_b64 v[232:233], v160 offset:65280
	ds_read_b64 v[234:235], v162 offset:0
	ds_read_b64 v[236:237], v155 offset:65280
	s_waitcnt lgkmcnt(11)
	v_add_f32_e32 v164, v214, v216
	v_mul_f32_e32 v214, 0.5, v164
	v_sub_f32_e32 v164, v215, v217
	v_mul_f32_e32 v216, 0.5, v164
	v_pk_mul_f32 v[216:217], v[218:219], v[216:217] op_sel:[1,0] op_sel_hi:[0,0]
	v_pk_fma_f32 v[158:159], v[218:219], v[214:215], v[216:217] neg_lo:[0,0,1] neg_hi:[0,0,1]
	v_pk_fma_f32 v[214:215], v[218:219], v[214:215], v[216:217] op_sel_hi:[1,0,1]
	s_nop 0
	v_mov_b32_e32 v159, v215
	v_pk_mul_f32 v[218:219], v[158:159], s[24:25]
	ds_write_b64 v155, v[218:219] offset:52224
	s_waitcnt lgkmcnt(9)
	v_add_f32_e32 v164, v220, v222
	v_mul_f32_e32 v220, 0.5, v164
	v_sub_f32_e32 v164, v221, v223
	v_mul_f32_e32 v222, 0.5, v164
	v_pk_mul_f32 v[222:223], v[224:225], v[222:223] op_sel:[1,0] op_sel_hi:[0,0]
	v_pk_fma_f32 v[158:159], v[224:225], v[220:221], v[222:223] neg_lo:[0,0,1] neg_hi:[0,0,1]
	v_pk_fma_f32 v[220:221], v[224:225], v[220:221], v[222:223] op_sel_hi:[1,0,1]
	s_nop 0
	v_mov_b32_e32 v159, v221
	v_pk_mul_f32 v[224:225], v[158:159], s[24:25]
	ds_write_b64 v155, v[224:225] offset:56576
	s_waitcnt lgkmcnt(5)
	v_add_f32_e32 v164, v226, v228
	v_mul_f32_e32 v226, 0.5, v164
	v_sub_f32_e32 v164, v227, v229
	v_mul_f32_e32 v228, 0.5, v164
	v_pk_mul_f32 v[228:229], v[230:231], v[228:229] op_sel:[1,0] op_sel_hi:[0,0]
	v_pk_fma_f32 v[158:159], v[230:231], v[226:227], v[228:229] neg_lo:[0,0,1] neg_hi:[0,0,1]
	v_pk_fma_f32 v[226:227], v[230:231], v[226:227], v[228:229] op_sel_hi:[1,0,1]
	s_nop 0
	v_mov_b32_e32 v159, v227
	v_pk_mul_f32 v[230:231], v[158:159], s[24:25]
	ds_write_b64 v155, v[230:231] offset:60928
	s_waitcnt lgkmcnt(3)
	v_add_f32_e32 v164, v232, v234
	v_mul_f32_e32 v232, 0.5, v164
	v_sub_f32_e32 v164, v233, v235
	v_mul_f32_e32 v234, 0.5, v164
	v_pk_mul_f32 v[234:235], v[236:237], v[234:235] op_sel:[1,0] op_sel_hi:[0,0]
	v_pk_fma_f32 v[158:159], v[236:237], v[232:233], v[234:235] neg_lo:[0,0,1] neg_hi:[0,0,1]
	v_pk_fma_f32 v[232:233], v[236:237], v[232:233], v[234:235] op_sel_hi:[1,0,1]
	s_nop 0
	v_mov_b32_e32 v159, v233
	v_pk_mul_f32 v[236:237], v[158:159], s[24:25]
	ds_write_b64 v155, v[236:237] offset:65280
	s_mov_b32 s0, 16
	s_cmp_lg_u32 s0, 16
	s_waitcnt lgkmcnt(0)
	s_barrier
	s_and_saveexec_b64 s[0:1], s[40:41]
	s_cbranch_execz .LBB0_436
	ds_read_b64 v[0:1], v37 offset:2176
	ds_read_b64 v[2:3], v37 offset:4352
	ds_read_b64 v[4:5], v37 offset:6528
	ds_read_b64 v[6:7], v37 offset:8704
	ds_read_b64 v[8:9], v37 offset:10880
	ds_read_b64 v[10:11], v37 offset:13056
	ds_read_b64 v[12:13], v37 offset:15232
	ds_read_b64 v[14:15], v37 offset:17408
	ds_read_b64 v[16:17], v37 offset:19584
	ds_read_b64 v[18:19], v37 offset:21760
	ds_read_b64 v[20:21], v37 offset:23936
	ds_read_b64 v[22:23], v37 offset:26112
	ds_read_b64 v[24:25], v37 offset:34816
	ds_read_b64 v[26:27], v37 offset:36992
	ds_read_b64 v[28:29], v37 offset:39168
	ds_read_b64 v[30:31], v37 offset:41344
	ds_read_b64 v[102:103], v37 offset:43520
	ds_read_b64 v[110:111], v37 offset:45696
	ds_read_b64 v[118:119], v37 offset:47872
	ds_read_b64 v[120:121], v37 offset:50048
	ds_read_b64 v[122:123], v37 offset:52224
	ds_read_b64 v[124:125], v37 offset:54400
	ds_read_b64 v[126:127], v37 offset:56576
	ds_read_b64 v[128:129], v37 offset:58752
	ds_read_b64 v[130:131], v37
	ds_read_b64 v[132:133], v37 offset:60928
	ds_read_b64 v[134:135], v37 offset:63104
	ds_read_b64 v[136:137], v37 offset:65280
	s_mov_b32 s11, s14
	s_waitcnt lgkmcnt(3)
	v_pk_add_f32 v[158:159], v[130:131], v[24:25]
	v_pk_add_f32 v[24:25], v[130:131], v[24:25] neg_lo:[0,1] neg_hi:[0,1]
	v_pk_add_f32 v[130:131], v[0:1], v[26:27]
	v_pk_add_f32 v[0:1], v[0:1], v[26:27] neg_lo:[0,1] neg_hi:[0,1]
	s_mov_b32 s13, s86
	v_pk_mul_f32 v[26:27], v[0:1], s[16:17]
	s_mov_b32 s4, s21
	v_pk_fma_f32 v[0:1], v[0:1], s[6:7], v[26:27] op_sel:[0,0,1] op_sel_hi:[1,0,0]
	v_pk_add_f32 v[26:27], v[2:3], v[28:29]
	v_pk_add_f32 v[2:3], v[2:3], v[28:29] neg_lo:[0,1] neg_hi:[0,1]
	s_mov_b32 s35, s30
	v_pk_mul_f32 v[28:29], v[2:3], s[18:19]
	s_mov_b32 s8, s19
	v_pk_fma_f32 v[2:3], v[2:3], s[30:31], v[28:29] op_sel:[0,0,1] op_sel_hi:[1,0,0]
	v_pk_add_f32 v[28:29], v[4:5], v[30:31]
	v_pk_add_f32 v[4:5], v[4:5], v[30:31] neg_lo:[0,1] neg_hi:[0,1]
	s_mov_b32 s77, s6
	v_pk_mul_f32 v[30:31], v[4:5], s[20:21]
	s_mov_b32 s28, s17
	v_pk_fma_f32 v[4:5], v[4:5], s[86:87], v[30:31] op_sel:[0,0,1] op_sel_hi:[1,0,0]
	v_pk_add_f32 v[30:31], v[6:7], v[102:103]
	v_pk_add_f32 v[6:7], v[6:7], v[102:103] neg_lo:[0,1] neg_hi:[0,1]
	v_add_u32_e32 v47, 0x10780, v37
	v_pk_mul_f32 v[102:103], v[6:7], s[10:11]
	ds_read_b64 v[138:139], v37 offset:28288
	ds_read_b64 v[140:141], v37 offset:30464
	ds_read_b64 v[142:143], v37 offset:32640
	ds_read_b64 v[144:145], v47
	v_pk_fma_f32 v[6:7], v[6:7], s[14:15], v[102:103] op_sel:[0,0,1] op_sel_hi:[1,0,0]
	v_pk_add_f32 v[102:103], v[8:9], v[110:111]
	v_pk_add_f32 v[8:9], v[8:9], v[110:111] neg_lo:[0,1] neg_hi:[0,1]
	s_nop 0
	v_pk_mul_f32 v[110:111], v[8:9], s[12:13]
	s_nop 0
	v_pk_fma_f32 v[8:9], v[8:9], s[4:5], v[110:111] op_sel:[0,0,1] op_sel_hi:[1,0,0]
	v_pk_add_f32 v[110:111], v[10:11], v[118:119]
	v_pk_add_f32 v[10:11], v[10:11], v[118:119] neg_lo:[0,1] neg_hi:[0,1]
	s_nop 0
	v_pk_mul_f32 v[118:119], v[10:11], s[34:35]
	s_nop 0
	v_pk_fma_f32 v[10:11], v[10:11], s[8:9], v[118:119] op_sel:[0,0,1] op_sel_hi:[1,0,0]
	v_pk_add_f32 v[118:119], v[12:13], v[120:121]
	v_pk_add_f32 v[12:13], v[12:13], v[120:121] neg_lo:[0,1] neg_hi:[0,1]
	s_nop 0
	v_pk_mul_f32 v[120:121], v[12:13], s[76:77]
	s_nop 0
	v_pk_fma_f32 v[12:13], v[12:13], s[28:29], v[120:121] op_sel:[0,0,1] op_sel_hi:[1,0,0]
	v_pk_add_f32 v[120:121], v[14:15], v[122:123]
	v_pk_add_f32 v[14:15], v[14:15], v[122:123] neg_lo:[0,1] neg_hi:[0,1]
	v_pk_add_f32 v[122:123], v[16:17], v[124:125]
	v_pk_add_f32 v[16:17], v[16:17], v[124:125] neg_lo:[0,1] neg_hi:[0,1]
	s_nop 0
	v_pk_mul_f32 v[124:125], v[16:17], s[76:77]
	s_nop 0
	v_pk_fma_f32 v[16:17], v[16:17], s[28:29], v[124:125] op_sel:[0,0,1] op_sel_hi:[1,0,0] neg_lo:[1,0,0] neg_hi:[1,0,0]
	v_pk_add_f32 v[124:125], v[18:19], v[126:127]
	v_pk_add_f32 v[18:19], v[18:19], v[126:127] neg_lo:[0,1] neg_hi:[0,1]
	s_nop 0
	v_pk_mul_f32 v[126:127], v[18:19], s[34:35]
	s_nop 0
	v_pk_fma_f32 v[18:19], v[18:19], s[8:9], v[126:127] op_sel:[0,0,1] op_sel_hi:[1,0,0] neg_lo:[1,0,0] neg_hi:[1,0,0]
	v_pk_add_f32 v[126:127], v[20:21], v[128:129]
	v_pk_add_f32 v[20:21], v[20:21], v[128:129] neg_lo:[0,1] neg_hi:[0,1]
	s_nop 0
	v_pk_mul_f32 v[128:129], v[20:21], s[12:13]
	s_nop 0
	v_pk_fma_f32 v[20:21], v[20:21], s[4:5], v[128:129] op_sel:[0,0,1] op_sel_hi:[1,0,0] neg_lo:[1,0,0] neg_hi:[1,0,0]
	s_waitcnt lgkmcnt(6)
	v_pk_add_f32 v[128:129], v[22:23], v[132:133]
	v_pk_add_f32 v[22:23], v[22:23], v[132:133] neg_lo:[0,1] neg_hi:[0,1]
	s_nop 0
	v_pk_mul_f32 v[132:133], v[22:23], s[10:11]
	s_nop 0
	v_pk_fma_f32 v[22:23], v[22:23], s[14:15], v[132:133] op_sel:[0,0,1] op_sel_hi:[1,0,0] neg_lo:[1,0,0] neg_hi:[1,0,0]
	s_waitcnt lgkmcnt(3)
	v_pk_add_f32 v[132:133], v[138:139], v[134:135]
	v_pk_add_f32 v[134:135], v[138:139], v[134:135] neg_lo:[0,1] neg_hi:[0,1]
	s_nop 0
	v_pk_mul_f32 v[138:139], v[134:135], s[20:21]
	s_nop 0
	v_pk_fma_f32 v[134:135], v[134:135], s[86:87], v[138:139] op_sel:[0,0,1] op_sel_hi:[1,0,0] neg_lo:[1,0,0] neg_hi:[1,0,0]
	s_waitcnt lgkmcnt(2)
	v_pk_add_f32 v[138:139], v[140:141], v[136:137]
	v_pk_add_f32 v[136:137], v[140:141], v[136:137] neg_lo:[0,1] neg_hi:[0,1]
	s_nop 0
	v_pk_mul_f32 v[140:141], v[136:137], s[18:19]
	s_nop 0
	v_pk_fma_f32 v[136:137], v[136:137], s[30:31], v[140:141] op_sel:[0,0,1] op_sel_hi:[1,0,0] neg_lo:[1,0,0] neg_hi:[1,0,0]
	s_waitcnt lgkmcnt(0)
	v_pk_add_f32 v[140:141], v[142:143], v[144:145]
	v_pk_add_f32 v[142:143], v[142:143], v[144:145] neg_lo:[0,1] neg_hi:[0,1]
	s_nop 0
	v_pk_mul_f32 v[144:145], v[142:143], s[16:17]
	s_nop 0
	v_pk_fma_f32 v[142:143], v[142:143], s[6:7], v[144:145] op_sel:[0,0,1] op_sel_hi:[1,0,0] neg_lo:[1,0,0] neg_hi:[1,0,0]
	v_pk_add_f32 v[144:145], v[158:159], v[120:121]
	v_pk_add_f32 v[120:121], v[158:159], v[120:121] neg_lo:[0,1] neg_hi:[0,1]
	v_pk_add_f32 v[158:159], v[130:131], v[122:123]
	v_pk_add_f32 v[122:123], v[130:131], v[122:123] neg_lo:[0,1] neg_hi:[0,1]
	s_nop 0
	v_pk_mul_f32 v[130:131], v[122:123], s[18:19]
	s_nop 0
	v_pk_fma_f32 v[122:123], v[122:123], s[30:31], v[130:131] op_sel:[0,0,1] op_sel_hi:[1,0,0]
	v_pk_add_f32 v[130:131], v[26:27], v[124:125]
	v_pk_add_f32 v[26:27], v[26:27], v[124:125] neg_lo:[0,1] neg_hi:[0,1]
	s_nop 0
	v_pk_mul_f32 v[124:125], v[26:27], s[10:11]
	s_nop 0
	v_pk_fma_f32 v[26:27], v[26:27], s[14:15], v[124:125] op_sel:[0,0,1] op_sel_hi:[1,0,0]
	v_pk_add_f32 v[124:125], v[28:29], v[126:127]
	v_pk_add_f32 v[28:29], v[28:29], v[126:127] neg_lo:[0,1] neg_hi:[0,1]
	s_nop 0
	v_pk_mul_f32 v[126:127], v[28:29], s[34:35]
	s_nop 0
	v_pk_fma_f32 v[28:29], v[28:29], s[8:9], v[126:127] op_sel:[0,0,1] op_sel_hi:[1,0,0]
	v_pk_add_f32 v[126:127], v[30:31], v[128:129]
	v_pk_add_f32 v[30:31], v[30:31], v[128:129] neg_lo:[0,1] neg_hi:[0,1]
	v_pk_add_f32 v[128:129], v[102:103], v[132:133]
	v_pk_add_f32 v[102:103], v[102:103], v[132:133] neg_lo:[0,1] neg_hi:[0,1]
	s_nop 0
	v_pk_mul_f32 v[132:133], v[102:103], s[34:35]
	s_nop 0
	v_pk_fma_f32 v[102:103], v[102:103], s[8:9], v[132:133] op_sel:[0,0,1] op_sel_hi:[1,0,0] neg_lo:[1,0,0] neg_hi:[1,0,0]
	v_pk_add_f32 v[132:133], v[110:111], v[138:139]
	v_pk_add_f32 v[110:111], v[110:111], v[138:139] neg_lo:[0,1] neg_hi:[0,1]
	s_nop 0
	v_pk_mul_f32 v[138:139], v[110:111], s[10:11]
	s_nop 0
	v_pk_fma_f32 v[110:111], v[110:111], s[14:15], v[138:139] op_sel:[0,0,1] op_sel_hi:[1,0,0] neg_lo:[1,0,0] neg_hi:[1,0,0]
	v_pk_add_f32 v[138:139], v[118:119], v[140:141]
	v_pk_add_f32 v[118:119], v[118:119], v[140:141] neg_lo:[0,1] neg_hi:[0,1]
	s_nop 0
	v_pk_mul_f32 v[140:141], v[118:119], s[18:19]
	s_nop 0
	v_pk_fma_f32 v[118:119], v[118:119], s[30:31], v[140:141] op_sel:[0,0,1] op_sel_hi:[1,0,0] neg_lo:[1,0,0] neg_hi:[1,0,0]
	v_pk_add_f32 v[140:141], v[24:25], v[14:15] op_sel:[0,1] op_sel_hi:[1,0] neg_hi:[0,1]
	v_pk_add_f32 v[14:15], v[24:25], v[14:15] op_sel:[0,1] op_sel_hi:[1,0] neg_lo:[0,1]
	v_pk_add_f32 v[24:25], v[0:1], v[16:17]
	v_pk_add_f32 v[0:1], v[0:1], v[16:17] neg_lo:[0,1] neg_hi:[0,1]
	s_nop 0
	v_pk_mul_f32 v[16:17], v[0:1], s[18:19]
	s_nop 0
	v_pk_fma_f32 v[0:1], v[0:1], s[30:31], v[16:17] op_sel:[0,0,1] op_sel_hi:[1,0,0]
	v_pk_add_f32 v[16:17], v[2:3], v[18:19]
	v_pk_add_f32 v[2:3], v[2:3], v[18:19] neg_lo:[0,1] neg_hi:[0,1]
	s_nop 0
	v_pk_mul_f32 v[18:19], v[2:3], s[10:11]
	s_nop 0
	v_pk_fma_f32 v[2:3], v[2:3], s[14:15], v[18:19] op_sel:[0,0,1] op_sel_hi:[1,0,0]
	v_pk_add_f32 v[18:19], v[4:5], v[20:21]
	v_pk_add_f32 v[4:5], v[4:5], v[20:21] neg_lo:[0,1] neg_hi:[0,1]
	s_nop 0
	v_pk_mul_f32 v[20:21], v[4:5], s[34:35]
	s_nop 0
	v_pk_fma_f32 v[4:5], v[4:5], s[8:9], v[20:21] op_sel:[0,0,1] op_sel_hi:[1,0,0]
	v_pk_add_f32 v[20:21], v[6:7], v[22:23]
	v_pk_add_f32 v[6:7], v[6:7], v[22:23] neg_lo:[0,1] neg_hi:[0,1]
	v_pk_add_f32 v[22:23], v[8:9], v[134:135]
	v_pk_add_f32 v[8:9], v[8:9], v[134:135] neg_lo:[0,1] neg_hi:[0,1]
	s_nop 0
	v_pk_mul_f32 v[134:135], v[8:9], s[34:35]
	s_nop 0
	v_pk_fma_f32 v[8:9], v[8:9], s[8:9], v[134:135] op_sel:[0,0,1] op_sel_hi:[1,0,0] neg_lo:[1,0,0] neg_hi:[1,0,0]
	v_pk_add_f32 v[134:135], v[10:11], v[136:137]
	v_pk_add_f32 v[10:11], v[10:11], v[136:137] neg_lo:[0,1] neg_hi:[0,1]
	s_nop 0
	v_pk_mul_f32 v[136:137], v[10:11], s[10:11]
	s_nop 0
	v_pk_fma_f32 v[10:11], v[10:11], s[14:15], v[136:137] op_sel:[0,0,1] op_sel_hi:[1,0,0] neg_lo:[1,0,0] neg_hi:[1,0,0]
	v_pk_add_f32 v[136:137], v[12:13], v[142:143]
	v_pk_add_f32 v[12:13], v[12:13], v[142:143] neg_lo:[0,1] neg_hi:[0,1]
	s_nop 0
	v_pk_mul_f32 v[142:143], v[12:13], s[18:19]
	s_nop 0
	v_pk_fma_f32 v[12:13], v[12:13], s[30:31], v[142:143] op_sel:[0,0,1] op_sel_hi:[1,0,0] neg_lo:[1,0,0] neg_hi:[1,0,0]
	v_pk_add_f32 v[142:143], v[144:145], v[126:127]
	v_pk_add_f32 v[126:127], v[144:145], v[126:127] neg_lo:[0,1] neg_hi:[0,1]
	v_pk_add_f32 v[144:145], v[158:159], v[128:129]
	v_pk_add_f32 v[128:129], v[158:159], v[128:129] neg_lo:[0,1] neg_hi:[0,1]
	s_nop 0
	v_pk_mul_f32 v[158:159], v[128:129], s[10:11]
	s_nop 0
	v_pk_fma_f32 v[128:129], v[128:129], s[14:15], v[158:159] op_sel:[0,0,1] op_sel_hi:[1,0,0]
	v_pk_add_f32 v[158:159], v[130:131], v[132:133]
	v_pk_add_f32 v[130:131], v[130:131], v[132:133] neg_lo:[0,1] neg_hi:[0,1]
	v_pk_add_f32 v[132:133], v[124:125], v[138:139]
	v_pk_add_f32 v[124:125], v[124:125], v[138:139] neg_lo:[0,1] neg_hi:[0,1]
	s_nop 0
	v_pk_mul_f32 v[138:139], v[124:125], s[10:11]
	s_nop 0
	v_pk_fma_f32 v[124:125], v[124:125], s[14:15], v[138:139] op_sel:[0,0,1] op_sel_hi:[1,0,0] neg_lo:[1,0,0] neg_hi:[1,0,0]
	v_pk_add_f32 v[138:139], v[120:121], v[30:31] op_sel:[0,1] op_sel_hi:[1,0] neg_hi:[0,1]
	v_pk_add_f32 v[30:31], v[120:121], v[30:31] op_sel:[0,1] op_sel_hi:[1,0] neg_lo:[0,1]
	v_pk_add_f32 v[120:121], v[122:123], v[102:103]
	v_pk_add_f32 v[102:103], v[122:123], v[102:103] neg_lo:[0,1] neg_hi:[0,1]
	v_pk_add_f32 v[160:161], v[128:129], v[124:125]
	v_pk_mul_f32 v[122:123], v[102:103], s[10:11]
	v_pk_add_f32 v[124:125], v[128:129], v[124:125] neg_lo:[0,1] neg_hi:[0,1]
	v_pk_fma_f32 v[102:103], v[102:103], s[14:15], v[122:123] op_sel:[0,0,1] op_sel_hi:[1,0,0]
	v_pk_add_f32 v[122:123], v[26:27], v[110:111]
	v_pk_add_f32 v[26:27], v[26:27], v[110:111] neg_lo:[0,1] neg_hi:[0,1]
	v_pk_add_f32 v[110:111], v[28:29], v[118:119]
	v_pk_add_f32 v[28:29], v[28:29], v[118:119] neg_lo:[0,1] neg_hi:[0,1]
	s_nop 0
	v_pk_mul_f32 v[118:119], v[28:29], s[10:11]
	v_pk_add_f32 v[166:167], v[120:121], v[110:111]
	v_pk_fma_f32 v[28:29], v[28:29], s[14:15], v[118:119] op_sel:[0,0,1] op_sel_hi:[1,0,0] neg_lo:[1,0,0] neg_hi:[1,0,0]
	v_pk_add_f32 v[118:119], v[140:141], v[20:21]
	v_pk_add_f32 v[20:21], v[140:141], v[20:21] neg_lo:[0,1] neg_hi:[0,1]
	v_pk_add_f32 v[140:141], v[24:25], v[22:23]
	v_pk_add_f32 v[22:23], v[24:25], v[22:23] neg_lo:[0,1] neg_hi:[0,1]
	v_pk_add_f32 v[110:111], v[120:121], v[110:111] neg_lo:[0,1] neg_hi:[0,1]
	v_pk_mul_f32 v[24:25], v[22:23], s[10:11]
	v_pk_add_f32 v[168:169], v[30:31], v[26:27] op_sel:[0,1] op_sel_hi:[1,0] neg_hi:[0,1]
	v_pk_fma_f32 v[22:23], v[22:23], s[14:15], v[24:25] op_sel:[0,0,1] op_sel_hi:[1,0,0]
	v_pk_add_f32 v[24:25], v[16:17], v[134:135]
	v_pk_add_f32 v[16:17], v[16:17], v[134:135] neg_lo:[0,1] neg_hi:[0,1]
	v_pk_add_f32 v[134:135], v[18:19], v[136:137]
	v_pk_add_f32 v[18:19], v[18:19], v[136:137] neg_lo:[0,1] neg_hi:[0,1]
	s_nop 0
	v_pk_mul_f32 v[136:137], v[18:19], s[10:11]
	v_pk_add_f32 v[26:27], v[30:31], v[26:27] op_sel:[0,1] op_sel_hi:[1,0] neg_lo:[0,1]
	v_pk_fma_f32 v[18:19], v[18:19], s[14:15], v[136:137] op_sel:[0,0,1] op_sel_hi:[1,0,0] neg_lo:[1,0,0] neg_hi:[1,0,0]
	v_pk_add_f32 v[136:137], v[14:15], v[6:7] op_sel:[0,1] op_sel_hi:[1,0] neg_hi:[0,1]
	v_pk_add_f32 v[6:7], v[14:15], v[6:7] op_sel:[0,1] op_sel_hi:[1,0] neg_lo:[0,1]
	v_pk_add_f32 v[14:15], v[0:1], v[8:9]
	v_pk_add_f32 v[0:1], v[0:1], v[8:9] neg_lo:[0,1] neg_hi:[0,1]
	v_pk_add_f32 v[30:31], v[102:103], v[28:29]
	v_pk_mul_f32 v[8:9], v[0:1], s[10:11]
	v_pk_add_f32 v[28:29], v[102:103], v[28:29] neg_lo:[0,1] neg_hi:[0,1]
	v_pk_fma_f32 v[0:1], v[0:1], s[14:15], v[8:9] op_sel:[0,0,1] op_sel_hi:[1,0,0]
	v_pk_add_f32 v[8:9], v[2:3], v[10:11]
	v_pk_add_f32 v[2:3], v[2:3], v[10:11] neg_lo:[0,1] neg_hi:[0,1]
	v_pk_add_f32 v[10:11], v[4:5], v[12:13]
	v_pk_add_f32 v[4:5], v[4:5], v[12:13] neg_lo:[0,1] neg_hi:[0,1]
	s_nop 0
	v_pk_mul_f32 v[12:13], v[4:5], s[10:11]
	v_pk_add_f32 v[170:171], v[118:119], v[24:25]
	v_pk_fma_f32 v[4:5], v[4:5], s[14:15], v[12:13] op_sel:[0,0,1] op_sel_hi:[1,0,0] neg_lo:[1,0,0] neg_hi:[1,0,0]
	v_pk_add_f32 v[12:13], v[142:143], v[158:159]
	v_pk_add_f32 v[142:143], v[142:143], v[158:159] neg_lo:[0,1] neg_hi:[0,1]
	v_pk_add_f32 v[158:159], v[144:145], v[132:133]
	v_pk_add_f32 v[132:133], v[144:145], v[132:133] neg_lo:[0,1] neg_hi:[0,1]
	v_pk_add_f32 v[182:183], v[118:119], v[24:25] neg_lo:[0,1] neg_hi:[0,1]
	v_pk_add_f32 v[184:185], v[140:141], v[134:135]
	v_pk_add_f32 v[24:25], v[140:141], v[134:135] neg_lo:[0,1] neg_hi:[0,1]
	v_pk_add_f32 v[140:141], v[20:21], v[16:17] op_sel:[0,1] op_sel_hi:[1,0] neg_hi:[0,1]
	v_pk_add_f32 v[186:187], v[20:21], v[16:17] op_sel:[0,1] op_sel_hi:[1,0] neg_lo:[0,1]
	v_pk_add_f32 v[16:17], v[22:23], v[18:19] neg_lo:[0,1] neg_hi:[0,1]
	v_pk_add_f32 v[192:193], v[136:137], v[8:9]
	v_pk_add_f32 v[194:195], v[136:137], v[8:9] neg_lo:[0,1] neg_hi:[0,1]
	v_pk_add_f32 v[8:9], v[14:15], v[10:11] neg_lo:[0,1] neg_hi:[0,1]
	v_pk_add_f32 v[198:199], v[6:7], v[2:3] op_sel:[0,1] op_sel_hi:[1,0] neg_hi:[0,1]
	v_pk_add_f32 v[200:201], v[6:7], v[2:3] op_sel:[0,1] op_sel_hi:[1,0] neg_lo:[0,1]
	v_pk_add_f32 v[2:3], v[0:1], v[4:5]
	v_pk_add_f32 v[0:1], v[0:1], v[4:5] neg_lo:[0,1] neg_hi:[0,1]
	v_pk_add_f32 v[144:145], v[126:127], v[130:131] op_sel:[0,1] op_sel_hi:[1,0] neg_hi:[0,1]
	v_pk_add_f32 v[130:131], v[126:127], v[130:131] op_sel:[0,1] op_sel_hi:[1,0] neg_lo:[0,1]
	v_pk_mul_f32 v[162:163], v[124:125], s[22:23]
	v_pk_add_f32 v[164:165], v[138:139], v[122:123]
	v_pk_add_f32 v[138:139], v[138:139], v[122:123] neg_lo:[0,1] neg_hi:[0,1]
	v_pk_mul_f32 v[102:103], v[28:29], s[22:23]
	v_pk_mul_f32 v[134:135], v[24:25], s[22:23]
	v_pk_add_f32 v[188:189], v[22:23], v[18:19]
	v_pk_mul_f32 v[190:191], v[16:17], s[22:23]
	v_pk_add_f32 v[136:137], v[14:15], v[10:11]
	v_pk_mul_f32 v[196:197], v[8:9], s[22:23]
	v_pk_mul_f32 v[202:203], v[0:1], s[22:23]
	v_pk_add_f32 v[28:29], v[12:13], v[158:159]
	v_pk_add_f32 v[128:129], v[12:13], v[158:159] neg_lo:[0,1] neg_hi:[0,1]
	v_pk_add_f32 v[24:25], v[142:143], v[132:133] op_sel:[0,1] op_sel_hi:[1,0] neg_hi:[0,1]
	v_pk_add_f32 v[126:127], v[142:143], v[132:133] op_sel:[0,1] op_sel_hi:[1,0] neg_lo:[0,1]
	v_pk_add_f32 v[20:21], v[144:145], v[160:161]
	v_pk_add_f32 v[124:125], v[144:145], v[160:161] neg_lo:[0,1] neg_hi:[0,1]
	v_pk_add_f32 v[16:17], v[130:131], v[162:163] op_sel:[0,1] op_sel_hi:[1,0]
	v_pk_add_f32 v[122:123], v[130:131], v[162:163] op_sel:[0,1] op_sel_hi:[1,0] neg_lo:[0,1] neg_hi:[0,1]
	v_pk_add_f32 v[12:13], v[164:165], v[166:167]
	v_pk_add_f32 v[120:121], v[164:165], v[166:167] neg_lo:[0,1] neg_hi:[0,1]
	v_pk_add_f32 v[8:9], v[138:139], v[110:111] op_sel:[0,1] op_sel_hi:[1,0] neg_hi:[0,1]
	v_pk_add_f32 v[118:119], v[138:139], v[110:111] op_sel:[0,1] op_sel_hi:[1,0] neg_lo:[0,1]
	v_pk_add_f32 v[4:5], v[168:169], v[30:31]
	v_pk_add_f32 v[110:111], v[168:169], v[30:31] neg_lo:[0,1] neg_hi:[0,1]
	v_pk_add_f32 v[0:1], v[26:27], v[102:103] op_sel:[0,1] op_sel_hi:[1,0]
	v_pk_add_f32 v[102:103], v[26:27], v[102:103] op_sel:[0,1] op_sel_hi:[1,0] neg_lo:[0,1] neg_hi:[0,1]
	v_pk_add_f32 v[30:31], v[170:171], v[184:185]
	v_pk_add_f32 v[144:145], v[170:171], v[184:185] neg_lo:[0,1] neg_hi:[0,1]
	v_pk_add_f32 v[26:27], v[182:183], v[134:135] op_sel:[0,1] op_sel_hi:[1,0]
	v_pk_add_f32 v[142:143], v[182:183], v[134:135] op_sel:[0,1] op_sel_hi:[1,0] neg_lo:[0,1] neg_hi:[0,1]
	v_pk_add_f32 v[22:23], v[140:141], v[188:189]
	v_pk_add_f32 v[140:141], v[140:141], v[188:189] neg_lo:[0,1] neg_hi:[0,1]
	v_pk_add_f32 v[18:19], v[186:187], v[190:191] op_sel:[0,1] op_sel_hi:[1,0]
	v_pk_add_f32 v[138:139], v[186:187], v[190:191] op_sel:[0,1] op_sel_hi:[1,0] neg_lo:[0,1] neg_hi:[0,1]
	v_pk_add_f32 v[14:15], v[192:193], v[136:137]
	v_pk_add_f32 v[136:137], v[192:193], v[136:137] neg_lo:[0,1] neg_hi:[0,1]
	v_pk_add_f32 v[10:11], v[194:195], v[196:197] op_sel:[0,1] op_sel_hi:[1,0]
	v_pk_add_f32 v[134:135], v[194:195], v[196:197] op_sel:[0,1] op_sel_hi:[1,0] neg_lo:[0,1] neg_hi:[0,1]
	v_pk_add_f32 v[6:7], v[198:199], v[2:3]
	v_pk_add_f32 v[132:133], v[198:199], v[2:3] neg_lo:[0,1] neg_hi:[0,1]
	v_pk_add_f32 v[2:3], v[200:201], v[202:203] op_sel:[0,1] op_sel_hi:[1,0]
	v_pk_add_f32 v[130:131], v[200:201], v[202:203] op_sel:[0,1] op_sel_hi:[1,0] neg_lo:[0,1] neg_hi:[0,1]

.LBB0_485:
	v_add_u32_e32 v160, 0x11000, v155
	v_lshlrev_b32_e32 v161, 3, v154
	v_add_u32_e32 v161, 0x2200, v161
	v_add_u32_e32 v162, 0x11100, v156
	v_cmp_ne_u32_e32 vcc, 0, v32
	v_cndmask_b32_e32 v163, 0, v154, vcc
	v_lshlrev_b32_e32 v163, 3, v163
	v_add_u32_e32 v163, 0x11000, v163
	ds_read_b64 v[214:215], v160 offset:0
	ds_read_b64 v[216:217], v163
	ds_read_b64 v[218:219], v155 offset:0
	ds_read_b64 v[220:221], v160 offset:4352
	ds_read_b64 v[222:223], v162 offset:60928
	ds_read_b64 v[224:225], v155 offset:4352
	ds_read_b64 v[226:227], v160 offset:8704
	ds_read_b64 v[228:229], v161 offset:52224
	ds_read_b64 v[230:231], v155 offset:8704
	ds_read_b64 v[232:233], v160 offset:13056
	ds_read_b64 v[234:235], v162 offset:52224
	ds_read_b64 v[236:237], v155 offset:13056
	s_waitcnt lgkmcnt(9)
	v_add_f32_e32 v164, v215, v217
	v_sub_f32_e32 v165, v214, v216
	v_mul_f32_e32 v216, 0.5, v164
	v_mul_f32_e32 v214, -0.5, v165
	v_pk_mul_f32 v[214:215], v[218:219], v[214:215] op_sel:[1,0] op_sel_hi:[0,0]
	v_pk_fma_f32 v[158:159], v[218:219], v[216:217], v[214:215] neg_lo:[0,0,1] neg_hi:[0,0,1]
	v_pk_fma_f32 v[216:217], v[218:219], v[216:217], v[214:215] op_sel_hi:[1,0,1]
	s_nop 0
	v_mov_b32_e32 v159, v217
	v_pk_mul_f32 v[218:219], v[158:159], s[24:25]
	ds_write_b64 v155, v[218:219] offset:0
	s_waitcnt lgkmcnt(7)
	v_add_f32_e32 v164, v221, v223
	v_sub_f32_e32 v165, v220, v222
	v_mul_f32_e32 v222, 0.5, v164
	v_mul_f32_e32 v220, -0.5, v165
	v_pk_mul_f32 v[220:221], v[224:225], v[220:221] op_sel:[1,0] op_sel_hi:[0,0]
	v_pk_fma_f32 v[158:159], v[224:225], v[222:223], v[220:221] neg_lo:[0,0,1] neg_hi:[0,0,1]
	v_pk_fma_f32 v[222:223], v[224:225], v[222:223], v[220:221] op_sel_hi:[1,0,1]
	s_nop 0
	v_mov_b32_e32 v159, v223
	v_pk_mul_f32 v[224:225], v[158:159], s[24:25]
	ds_write_b64 v155, v[224:225] offset:4352
	ds_read_b64 v[182:183], v160 offset:17408
	ds_read_b64 v[184:185], v161 offset:43520
	ds_read_b64 v[186:187], v155 offset:17408
	ds_read_b64 v[188:189], v160 offset:21760
	ds_read_b64 v[190:191], v162 offset:43520
	ds_read_b64 v[192:193], v155 offset:21760
	s_waitcnt lgkmcnt(11)
	v_add_f32_e32 v164, v227, v229
	v_sub_f32_e32 v165, v226, v228
	v_mul_f32_e32 v228, 0.5, v164
	v_mul_f32_e32 v226, -0.5, v165
	v_pk_mul_f32 v[226:227], v[230:231], v[226:227] op_sel:[1,0] op_sel_hi:[0,0]
	v_pk_fma_f32 v[158:159], v[230:231], v[228:229], v[226:227] neg_lo:[0,0,1] neg_hi:[0,0,1]
	v_pk_fma_f32 v[228:229], v[230:231], v[228:229], v[226:227] op_sel_hi:[1,0,1]
	s_nop 0
	v_mov_b32_e32 v159, v229
	v_pk_mul_f32 v[230:231], v[158:159], s[24:25]
	ds_write_b64 v155, v[230:231] offset:8704
	s_waitcnt lgkmcnt(9)
	v_add_f32_e32 v164, v233, v235
	v_sub_f32_e32 v165, v232, v234
	v_mul_f32_e32 v234, 0.5, v164
	v_mul_f32_e32 v232, -0.5, v165
	v_pk_mul_f32 v[232:233], v[236:237], v[232:233] op_sel:[1,0] op_sel_hi:[0,0]
	v_pk_fma_f32 v[158:159], v[236:237], v[234:235], v[232:233] neg_lo:[0,0,1] neg_hi:[0,0,1]
	v_pk_fma_f32 v[234:235], v[236:237], v[234:235], v[232:233] op_sel_hi:[1,0,1]
	s_nop 0
	v_mov_b32_e32 v159, v235
	v_pk_mul_f32 v[236:237], v[158:159], s[24:25]
	ds_write_b64 v155, v[236:237] offset:13056
	ds_read_b64 v[214:215], v160 offset:26112
	ds_read_b64 v[216:217], v161 offset:34816
	ds_read_b64 v[218:219], v155 offset:26112
	ds_read_b64 v[220:221], v160 offset:30464
	ds_read_b64 v[222:223], v162 offset:34816
	ds_read_b64 v[224:225], v155 offset:30464
	s_waitcnt lgkmcnt(11)
	v_add_f32_e32 v164, v183, v185
	v_sub_f32_e32 v165, v182, v184
	v_mul_f32_e32 v184, 0.5, v164
	v_mul_f32_e32 v182, -0.5, v165
	v_pk_mul_f32 v[182:183], v[186:187], v[182:183] op_sel:[1,0] op_sel_hi:[0,0]
	v_pk_fma_f32 v[158:159], v[186:187], v[184:185], v[182:183] neg_lo:[0,0,1] neg_hi:[0,0,1]
	v_pk_fma_f32 v[184:185], v[186:187], v[184:185], v[182:183] op_sel_hi:[1,0,1]
	s_nop 0
	v_mov_b32_e32 v159, v185
	v_pk_mul_f32 v[186:187], v[158:159], s[24:25]
	ds_write_b64 v155, v[186:187] offset:17408
	s_waitcnt lgkmcnt(9)
	v_add_f32_e32 v164, v189, v191
	v_sub_f32_e32 v165, v188, v190
	v_mul_f32_e32 v190, 0.5, v164
	v_mul_f32_e32 v188, -0.5, v165
	v_pk_mul_f32 v[188:189], v[192:193], v[188:189] op_sel:[1,0] op_sel_hi:[0,0]
	v_pk_fma_f32 v[158:159], v[192:193], v[190:191], v[188:189] neg_lo:[0,0,1] neg_hi:[0,0,1]
	v_pk_fma_f32 v[190:191], v[192:193], v[190:191], v[188:189] op_sel_hi:[1,0,1]
	s_nop 0
	v_mov_b32_e32 v159, v191
	v_pk_mul_f32 v[192:193], v[158:159], s[24:25]
	ds_write_b64 v155, v[192:193] offset:21760
	ds_read_b64 v[226:227], v160 offset:34816
	ds_read_b64 v[228:229], v161 offset:26112
	ds_read_b64 v[230:231], v155 offset:34816
	ds_read_b64 v[232:233], v160 offset:39168
	ds_read_b64 v[234:235], v162 offset:26112
	ds_read_b64 v[236:237], v155 offset:39168
	s_waitcnt lgkmcnt(11)
	v_add_f32_e32 v164, v215, v217
	v_sub_f32_e32 v165, v214, v216
	v_mul_f32_e32 v216, 0.5, v164
	v_mul_f32_e32 v214, -0.5, v165
	v_pk_mul_f32 v[214:215], v[218:219], v[214:215] op_sel:[1,0] op_sel_hi:[0,0]
	v_pk_fma_f32 v[158:159], v[218:219], v[216:217], v[214:215] neg_lo:[0,0,1] neg_hi:[0,0,1]
	v_pk_fma_f32 v[216:217], v[218:219], v[216:217], v[214:215] op_sel_hi:[1,0,1]
	s_nop 0
	v_mov_b32_e32 v159, v217
	v_pk_mul_f32 v[218:219], v[158:159], s[24:25]
	ds_write_b64 v155, v[218:219] offset:26112
	s_waitcnt lgkmcnt(9)
	v_add_f32_e32 v164, v221, v223
	v_sub_f32_e32 v165, v220, v222
	v_mul_f32_e32 v222, 0.5, v164
	v_mul_f32_e32 v220, -0.5, v165
	v_pk_mul_f32 v[220:221], v[224:225], v[220:221] op_sel:[1,0] op_sel_hi:[0,0]
	v_pk_fma_f32 v[158:159], v[224:225], v[222:223], v[220:221] neg_lo:[0,0,1] neg_hi:[0,0,1]
	v_pk_fma_f32 v[222:223], v[224:225], v[222:223], v[220:221] op_sel_hi:[1,0,1]
	s_nop 0
	v_mov_b32_e32 v159, v223
	v_pk_mul_f32 v[224:225], v[158:159], s[24:25]
	ds_write_b64 v155, v[224:225] offset:30464
	ds_read_b64 v[182:183], v160 offset:43520
	ds_read_b64 v[184:185], v161 offset:17408
	ds_read_b64 v[186:187], v155 offset:43520
	ds_read_b64 v[188:189], v160 offset:47872
	ds_read_b64 v[190:191], v162 offset:17408
	ds_read_b64 v[192:193], v155 offset:47872
	s_waitcnt lgkmcnt(11)
	v_add_f32_e32 v164, v227, v229
	v_sub_f32_e32 v165, v226, v228
	v_mul_f32_e32 v228, 0.5, v164
	v_mul_f32_e32 v226, -0.5, v165
	v_pk_mul_f32 v[226:227], v[230:231], v[226:227] op_sel:[1,0] op_sel_hi:[0,0]
	v_pk_fma_f32 v[158:159], v[230:231], v[228:229], v[226:227] neg_lo:[0,0,1] neg_hi:[0,0,1]
	v_pk_fma_f32 v[228:229], v[230:231], v[228:229], v[226:227] op_sel_hi:[1,0,1]
	s_nop 0
	v_mov_b32_e32 v159, v229
	v_pk_mul_f32 v[230:231], v[158:159], s[24:25]
	ds_write_b64 v155, v[230:231] offset:34816
	s_waitcnt lgkmcnt(9)
	v_add_f32_e32 v164, v233, v235
	v_sub_f32_e32 v165, v232, v234
	v_mul_f32_e32 v234, 0.5, v164
	v_mul_f32_e32 v232, -0.5, v165
	v_pk_mul_f32 v[232:233], v[236:237], v[232:233] op_sel:[1,0] op_sel_hi:[0,0]
	v_pk_fma_f32 v[158:159], v[236:237], v[234:235], v[232:233] neg_lo:[0,0,1] neg_hi:[0,0,1]
	v_pk_fma_f32 v[234:235], v[236:237], v[234:235], v[232:233] op_sel_hi:[1,0,1]
	s_nop 0
	v_mov_b32_e32 v159, v235
	v_pk_mul_f32 v[236:237], v[158:159], s[24:25]
	ds_write_b64 v155, v[236:237] offset:39168
	ds_read_b64 v[214:215], v160 offset:52224
	ds_read_b64 v[216:217], v161 offset:8704
	ds_read_b64 v[218:219], v155 offset:52224
	ds_read_b64 v[220:221], v160 offset:56576
	ds_read_b64 v[222:223], v162 offset:8704
	ds_read_b64 v[224:225], v155 offset:56576
	s_waitcnt lgkmcnt(11)
	v_add_f32_e32 v164, v183, v185
	v_sub_f32_e32 v165, v182, v184
	v_mul_f32_e32 v184, 0.5, v164
	v_mul_f32_e32 v182, -0.5, v165
	v_pk_mul_f32 v[182:183], v[186:187], v[182:183] op_sel:[1,0] op_sel_hi:[0,0]
	v_pk_fma_f32 v[158:159], v[186:187], v[184:185], v[182:183] neg_lo:[0,0,1] neg_hi:[0,0,1]
	v_pk_fma_f32 v[184:185], v[186:187], v[184:185], v[182:183] op_sel_hi:[1,0,1]
	s_nop 0
	v_mov_b32_e32 v159, v185
	v_pk_mul_f32 v[186:187], v[158:159], s[24:25]
	ds_write_b64 v155, v[186:187] offset:43520
	s_waitcnt lgkmcnt(9)
	v_add_f32_e32 v164, v189, v191
	v_sub_f32_e32 v165, v188, v190
	v_mul_f32_e32 v190, 0.5, v164
	v_mul_f32_e32 v188, -0.5, v165
	v_pk_mul_f32 v[188:189], v[192:193], v[188:189] op_sel:[1,0] op_sel_hi:[0,0]
	v_pk_fma_f32 v[158:159], v[192:193], v[190:191], v[188:189] neg_lo:[0,0,1] neg_hi:[0,0,1]
	v_pk_fma_f32 v[190:191], v[192:193], v[190:191], v[188:189] op_sel_hi:[1,0,1]
	s_nop 0
	v_mov_b32_e32 v159, v191
	v_pk_mul_f32 v[192:193], v[158:159], s[24:25]
	ds_write_b64 v155, v[192:193] offset:47872
	ds_read_b64 v[226:227], v160 offset:60928
	ds_read_b64 v[228:229], v161 offset:0
	ds_read_b64 v[230:231], v155 offset:60928
	ds_read_b64 v[232:233], v160 offset:65280
	ds_read_b64 v[234:235], v162 offset:0
	ds_read_b64 v[236:237], v155 offset:65280
	s_waitcnt lgkmcnt(11)
	v_add_f32_e32 v164, v215, v217
	v_sub_f32_e32 v165, v214, v216
	v_mul_f32_e32 v216, 0.5, v164
	v_mul_f32_e32 v214, -0.5, v165
	v_pk_mul_f32 v[214:215], v[218:219], v[214:215] op_sel:[1,0] op_sel_hi:[0,0]
	v_pk_fma_f32 v[158:159], v[218:219], v[216:217], v[214:215] neg_lo:[0,0,1] neg_hi:[0,0,1]
	v_pk_fma_f32 v[216:217], v[218:219], v[216:217], v[214:215] op_sel_hi:[1,0,1]
	s_nop 0
	v_mov_b32_e32 v159, v217
	v_pk_mul_f32 v[218:219], v[158:159], s[24:25]
	ds_write_b64 v155, v[218:219] offset:52224
	s_waitcnt lgkmcnt(9)
	v_add_f32_e32 v164, v221, v223
	v_sub_f32_e32 v165, v220, v222
	v_mul_f32_e32 v222, 0.5, v164
	v_mul_f32_e32 v220, -0.5, v165
	v_pk_mul_f32 v[220:221], v[224:225], v[220:221] op_sel:[1,0] op_sel_hi:[0,0]
	v_pk_fma_f32 v[158:159], v[224:225], v[222:223], v[220:221] neg_lo:[0,0,1] neg_hi:[0,0,1]
	v_pk_fma_f32 v[222:223], v[224:225], v[222:223], v[220:221] op_sel_hi:[1,0,1]
	s_nop 0
	v_mov_b32_e32 v159, v223
	v_pk_mul_f32 v[224:225], v[158:159], s[24:25]
	ds_write_b64 v155, v[224:225] offset:56576
	s_waitcnt lgkmcnt(5)
	v_add_f32_e32 v164, v227, v229
	v_sub_f32_e32 v165, v226, v228
	v_mul_f32_e32 v228, 0.5, v164
	v_mul_f32_e32 v226, -0.5, v165
	v_pk_mul_f32 v[226:227], v[230:231], v[226:227] op_sel:[1,0] op_sel_hi:[0,0]
	v_pk_fma_f32 v[158:159], v[230:231], v[228:229], v[226:227] neg_lo:[0,0,1] neg_hi:[0,0,1]
	v_pk_fma_f32 v[228:229], v[230:231], v[228:229], v[226:227] op_sel_hi:[1,0,1]
	s_nop 0
	v_mov_b32_e32 v159, v229
	v_pk_mul_f32 v[230:231], v[158:159], s[24:25]
	ds_write_b64 v155, v[230:231] offset:60928
	s_waitcnt lgkmcnt(3)
	v_add_f32_e32 v164, v233, v235
	v_sub_f32_e32 v165, v232, v234
	v_mul_f32_e32 v234, 0.5, v164
	v_mul_f32_e32 v232, -0.5, v165
	v_pk_mul_f32 v[232:233], v[236:237], v[232:233] op_sel:[1,0] op_sel_hi:[0,0]
	v_pk_fma_f32 v[158:159], v[236:237], v[234:235], v[232:233] neg_lo:[0,0,1] neg_hi:[0,0,1]
	v_pk_fma_f32 v[234:235], v[236:237], v[234:235], v[232:233] op_sel_hi:[1,0,1]
	s_nop 0
	v_mov_b32_e32 v159, v235
	v_pk_mul_f32 v[236:237], v[158:159], s[24:25]
	ds_write_b64 v155, v[236:237] offset:65280
	s_mov_b32 s0, 16
	s_cmp_lg_u32 s0, 16
	s_waitcnt lgkmcnt(0)
	s_barrier
	s_and_saveexec_b64 s[0:1], s[40:41]
	s_cbranch_execz .LBB0_488
	ds_read_b64 v[0:1], v37 offset:2176
	ds_read_b64 v[2:3], v37 offset:4352
	ds_read_b64 v[4:5], v37 offset:6528
	ds_read_b64 v[6:7], v37 offset:8704
	ds_read_b64 v[8:9], v37 offset:10880
	ds_read_b64 v[10:11], v37 offset:13056
	ds_read_b64 v[12:13], v37 offset:15232
	ds_read_b64 v[14:15], v37 offset:17408
	ds_read_b64 v[16:17], v37 offset:19584
	ds_read_b64 v[18:19], v37 offset:21760
	ds_read_b64 v[20:21], v37 offset:23936
	ds_read_b64 v[22:23], v37 offset:26112
	ds_read_b64 v[24:25], v37 offset:34816
	ds_read_b64 v[26:27], v37 offset:36992
	ds_read_b64 v[28:29], v37 offset:39168
	ds_read_b64 v[30:31], v37 offset:41344
	ds_read_b64 v[82:83], v37 offset:43520
	ds_read_b64 v[84:85], v37 offset:45696
	ds_read_b64 v[118:119], v37 offset:47872
	ds_read_b64 v[120:121], v37 offset:50048
	ds_read_b64 v[122:123], v37 offset:52224
	ds_read_b64 v[124:125], v37 offset:54400
	ds_read_b64 v[126:127], v37 offset:56576
	ds_read_b64 v[128:129], v37 offset:58752
	ds_read_b64 v[130:131], v37
	ds_read_b64 v[132:133], v37 offset:60928
	ds_read_b64 v[134:135], v37 offset:63104
	ds_read_b64 v[136:137], v37 offset:65280
	s_mov_b32 s11, s14
	s_waitcnt lgkmcnt(3)
	v_pk_add_f32 v[158:159], v[130:131], v[24:25]
	v_pk_add_f32 v[24:25], v[130:131], v[24:25] neg_lo:[0,1] neg_hi:[0,1]
	v_pk_add_f32 v[130:131], v[0:1], v[26:27]
	v_pk_add_f32 v[0:1], v[0:1], v[26:27] neg_lo:[0,1] neg_hi:[0,1]
	s_mov_b32 s13, s86
	v_pk_mul_f32 v[26:27], v[0:1], s[16:17]
	s_mov_b32 s4, s21
	v_pk_fma_f32 v[0:1], v[0:1], s[6:7], v[26:27] op_sel:[0,0,1] op_sel_hi:[1,0,0]
	v_pk_add_f32 v[26:27], v[2:3], v[28:29]
	v_pk_add_f32 v[2:3], v[2:3], v[28:29] neg_lo:[0,1] neg_hi:[0,1]
	s_mov_b32 s35, s30
	v_pk_mul_f32 v[28:29], v[2:3], s[18:19]
	s_mov_b32 s8, s19
	v_pk_fma_f32 v[2:3], v[2:3], s[30:31], v[28:29] op_sel:[0,0,1] op_sel_hi:[1,0,0]
	v_pk_add_f32 v[28:29], v[4:5], v[30:31]
	v_pk_add_f32 v[4:5], v[4:5], v[30:31] neg_lo:[0,1] neg_hi:[0,1]
	s_mov_b32 s77, s6
	v_pk_mul_f32 v[30:31], v[4:5], s[20:21]
	s_mov_b32 s28, s17
	v_pk_fma_f32 v[4:5], v[4:5], s[86:87], v[30:31] op_sel:[0,0,1] op_sel_hi:[1,0,0]
	v_pk_add_f32 v[30:31], v[6:7], v[82:83]
	v_pk_add_f32 v[6:7], v[6:7], v[82:83] neg_lo:[0,1] neg_hi:[0,1]
	v_add_u32_e32 v47, 0x10780, v37
	v_pk_mul_f32 v[82:83], v[6:7], s[10:11]
	ds_read_b64 v[138:139], v37 offset:28288
	ds_read_b64 v[140:141], v37 offset:30464
	ds_read_b64 v[142:143], v37 offset:32640
	ds_read_b64 v[144:145], v47
	v_pk_fma_f32 v[6:7], v[6:7], s[14:15], v[82:83] op_sel:[0,0,1] op_sel_hi:[1,0,0]
	v_pk_add_f32 v[82:83], v[8:9], v[84:85]
	v_pk_add_f32 v[8:9], v[8:9], v[84:85] neg_lo:[0,1] neg_hi:[0,1]
	s_nop 0
	v_pk_mul_f32 v[84:85], v[8:9], s[12:13]
	s_nop 0
	v_pk_fma_f32 v[8:9], v[8:9], s[4:5], v[84:85] op_sel:[0,0,1] op_sel_hi:[1,0,0]
	v_pk_add_f32 v[84:85], v[10:11], v[118:119]
	v_pk_add_f32 v[10:11], v[10:11], v[118:119] neg_lo:[0,1] neg_hi:[0,1]
	s_nop 0
	v_pk_mul_f32 v[118:119], v[10:11], s[34:35]
	s_nop 0
	v_pk_fma_f32 v[10:11], v[10:11], s[8:9], v[118:119] op_sel:[0,0,1] op_sel_hi:[1,0,0]
	v_pk_add_f32 v[118:119], v[12:13], v[120:121]
	v_pk_add_f32 v[12:13], v[12:13], v[120:121] neg_lo:[0,1] neg_hi:[0,1]
	s_nop 0
	v_pk_mul_f32 v[120:121], v[12:13], s[76:77]
	s_nop 0
	v_pk_fma_f32 v[12:13], v[12:13], s[28:29], v[120:121] op_sel:[0,0,1] op_sel_hi:[1,0,0]
	v_pk_add_f32 v[120:121], v[14:15], v[122:123]
	v_pk_add_f32 v[14:15], v[14:15], v[122:123] neg_lo:[0,1] neg_hi:[0,1]
	v_pk_add_f32 v[122:123], v[16:17], v[124:125]
	v_pk_add_f32 v[16:17], v[16:17], v[124:125] neg_lo:[0,1] neg_hi:[0,1]
	s_nop 0
	v_pk_mul_f32 v[124:125], v[16:17], s[76:77]
	s_nop 0
	v_pk_fma_f32 v[16:17], v[16:17], s[28:29], v[124:125] op_sel:[0,0,1] op_sel_hi:[1,0,0] neg_lo:[1,0,0] neg_hi:[1,0,0]
	v_pk_add_f32 v[124:125], v[18:19], v[126:127]
	v_pk_add_f32 v[18:19], v[18:19], v[126:127] neg_lo:[0,1] neg_hi:[0,1]
	s_nop 0
	v_pk_mul_f32 v[126:127], v[18:19], s[34:35]
	s_nop 0
	v_pk_fma_f32 v[18:19], v[18:19], s[8:9], v[126:127] op_sel:[0,0,1] op_sel_hi:[1,0,0] neg_lo:[1,0,0] neg_hi:[1,0,0]
	v_pk_add_f32 v[126:127], v[20:21], v[128:129]
	v_pk_add_f32 v[20:21], v[20:21], v[128:129] neg_lo:[0,1] neg_hi:[0,1]
	s_nop 0
	v_pk_mul_f32 v[128:129], v[20:21], s[12:13]
	s_nop 0
	v_pk_fma_f32 v[20:21], v[20:21], s[4:5], v[128:129] op_sel:[0,0,1] op_sel_hi:[1,0,0] neg_lo:[1,0,0] neg_hi:[1,0,0]
	s_waitcnt lgkmcnt(6)
	v_pk_add_f32 v[128:129], v[22:23], v[132:133]
	v_pk_add_f32 v[22:23], v[22:23], v[132:133] neg_lo:[0,1] neg_hi:[0,1]
	s_nop 0
	v_pk_mul_f32 v[132:133], v[22:23], s[10:11]
	s_nop 0
	v_pk_fma_f32 v[22:23], v[22:23], s[14:15], v[132:133] op_sel:[0,0,1] op_sel_hi:[1,0,0] neg_lo:[1,0,0] neg_hi:[1,0,0]
	s_waitcnt lgkmcnt(3)
	v_pk_add_f32 v[132:133], v[138:139], v[134:135]
	v_pk_add_f32 v[134:135], v[138:139], v[134:135] neg_lo:[0,1] neg_hi:[0,1]
	s_nop 0
	v_pk_mul_f32 v[138:139], v[134:135], s[20:21]
	s_nop 0
	v_pk_fma_f32 v[134:135], v[134:135], s[86:87], v[138:139] op_sel:[0,0,1] op_sel_hi:[1,0,0] neg_lo:[1,0,0] neg_hi:[1,0,0]
	s_waitcnt lgkmcnt(2)
	v_pk_add_f32 v[138:139], v[140:141], v[136:137]
	v_pk_add_f32 v[136:137], v[140:141], v[136:137] neg_lo:[0,1] neg_hi:[0,1]
	s_nop 0
	v_pk_mul_f32 v[140:141], v[136:137], s[18:19]
	s_nop 0
	v_pk_fma_f32 v[136:137], v[136:137], s[30:31], v[140:141] op_sel:[0,0,1] op_sel_hi:[1,0,0] neg_lo:[1,0,0] neg_hi:[1,0,0]
	s_waitcnt lgkmcnt(0)
	v_pk_add_f32 v[140:141], v[142:143], v[144:145]
	v_pk_add_f32 v[142:143], v[142:143], v[144:145] neg_lo:[0,1] neg_hi:[0,1]
	s_nop 0
	v_pk_mul_f32 v[144:145], v[142:143], s[16:17]
	s_nop 0
	v_pk_fma_f32 v[142:143], v[142:143], s[6:7], v[144:145] op_sel:[0,0,1] op_sel_hi:[1,0,0] neg_lo:[1,0,0] neg_hi:[1,0,0]
	v_pk_add_f32 v[144:145], v[158:159], v[120:121]
	v_pk_add_f32 v[120:121], v[158:159], v[120:121] neg_lo:[0,1] neg_hi:[0,1]
	v_pk_add_f32 v[158:159], v[130:131], v[122:123]
	v_pk_add_f32 v[122:123], v[130:131], v[122:123] neg_lo:[0,1] neg_hi:[0,1]
	s_nop 0
	v_pk_mul_f32 v[130:131], v[122:123], s[18:19]
	s_nop 0
	v_pk_fma_f32 v[122:123], v[122:123], s[30:31], v[130:131] op_sel:[0,0,1] op_sel_hi:[1,0,0]
	v_pk_add_f32 v[130:131], v[26:27], v[124:125]
	v_pk_add_f32 v[26:27], v[26:27], v[124:125] neg_lo:[0,1] neg_hi:[0,1]
	s_nop 0
	v_pk_mul_f32 v[124:125], v[26:27], s[10:11]
	s_nop 0
	v_pk_fma_f32 v[26:27], v[26:27], s[14:15], v[124:125] op_sel:[0,0,1] op_sel_hi:[1,0,0]
	v_pk_add_f32 v[124:125], v[28:29], v[126:127]
	v_pk_add_f32 v[28:29], v[28:29], v[126:127] neg_lo:[0,1] neg_hi:[0,1]
	s_nop 0
	v_pk_mul_f32 v[126:127], v[28:29], s[34:35]
	s_nop 0
	v_pk_fma_f32 v[28:29], v[28:29], s[8:9], v[126:127] op_sel:[0,0,1] op_sel_hi:[1,0,0]
	v_pk_add_f32 v[126:127], v[30:31], v[128:129]
	v_pk_add_f32 v[30:31], v[30:31], v[128:129] neg_lo:[0,1] neg_hi:[0,1]
	v_pk_add_f32 v[128:129], v[82:83], v[132:133]
	v_pk_add_f32 v[82:83], v[82:83], v[132:133] neg_lo:[0,1] neg_hi:[0,1]
	s_nop 0
	v_pk_mul_f32 v[132:133], v[82:83], s[34:35]
	s_nop 0
	v_pk_fma_f32 v[82:83], v[82:83], s[8:9], v[132:133] op_sel:[0,0,1] op_sel_hi:[1,0,0] neg_lo:[1,0,0] neg_hi:[1,0,0]
	v_pk_add_f32 v[132:133], v[84:85], v[138:139]
	v_pk_add_f32 v[84:85], v[84:85], v[138:139] neg_lo:[0,1] neg_hi:[0,1]
	s_nop 0
	v_pk_mul_f32 v[138:139], v[84:85], s[10:11]
	s_nop 0
	v_pk_fma_f32 v[84:85], v[84:85], s[14:15], v[138:139] op_sel:[0,0,1] op_sel_hi:[1,0,0] neg_lo:[1,0,0] neg_hi:[1,0,0]
	v_pk_add_f32 v[138:139], v[118:119], v[140:141]
	v_pk_add_f32 v[118:119], v[118:119], v[140:141] neg_lo:[0,1] neg_hi:[0,1]
	s_nop 0
	v_pk_mul_f32 v[140:141], v[118:119], s[18:19]
	s_nop 0
	v_pk_fma_f32 v[118:119], v[118:119], s[30:31], v[140:141] op_sel:[0,0,1] op_sel_hi:[1,0,0] neg_lo:[1,0,0] neg_hi:[1,0,0]
	v_pk_add_f32 v[140:141], v[24:25], v[14:15] op_sel:[0,1] op_sel_hi:[1,0] neg_hi:[0,1]
	v_pk_add_f32 v[14:15], v[24:25], v[14:15] op_sel:[0,1] op_sel_hi:[1,0] neg_lo:[0,1]
	v_pk_add_f32 v[24:25], v[0:1], v[16:17]
	v_pk_add_f32 v[0:1], v[0:1], v[16:17] neg_lo:[0,1] neg_hi:[0,1]
	s_nop 0
	v_pk_mul_f32 v[16:17], v[0:1], s[18:19]
	s_nop 0
	v_pk_fma_f32 v[0:1], v[0:1], s[30:31], v[16:17] op_sel:[0,0,1] op_sel_hi:[1,0,0]
	v_pk_add_f32 v[16:17], v[2:3], v[18:19]
	v_pk_add_f32 v[2:3], v[2:3], v[18:19] neg_lo:[0,1] neg_hi:[0,1]
	s_nop 0
	v_pk_mul_f32 v[18:19], v[2:3], s[10:11]
	s_nop 0
	v_pk_fma_f32 v[2:3], v[2:3], s[14:15], v[18:19] op_sel:[0,0,1] op_sel_hi:[1,0,0]
	v_pk_add_f32 v[18:19], v[4:5], v[20:21]
	v_pk_add_f32 v[4:5], v[4:5], v[20:21] neg_lo:[0,1] neg_hi:[0,1]
	s_nop 0
	v_pk_mul_f32 v[20:21], v[4:5], s[34:35]
	s_nop 0
	v_pk_fma_f32 v[4:5], v[4:5], s[8:9], v[20:21] op_sel:[0,0,1] op_sel_hi:[1,0,0]
	v_pk_add_f32 v[20:21], v[6:7], v[22:23]
	v_pk_add_f32 v[6:7], v[6:7], v[22:23] neg_lo:[0,1] neg_hi:[0,1]
	v_pk_add_f32 v[22:23], v[8:9], v[134:135]
	v_pk_add_f32 v[8:9], v[8:9], v[134:135] neg_lo:[0,1] neg_hi:[0,1]
	s_nop 0
	v_pk_mul_f32 v[134:135], v[8:9], s[34:35]
	s_nop 0
	v_pk_fma_f32 v[8:9], v[8:9], s[8:9], v[134:135] op_sel:[0,0,1] op_sel_hi:[1,0,0] neg_lo:[1,0,0] neg_hi:[1,0,0]
	v_pk_add_f32 v[134:135], v[10:11], v[136:137]
	v_pk_add_f32 v[10:11], v[10:11], v[136:137] neg_lo:[0,1] neg_hi:[0,1]
	s_nop 0
	v_pk_mul_f32 v[136:137], v[10:11], s[10:11]
	s_nop 0
	v_pk_fma_f32 v[10:11], v[10:11], s[14:15], v[136:137] op_sel:[0,0,1] op_sel_hi:[1,0,0] neg_lo:[1,0,0] neg_hi:[1,0,0]
	v_pk_add_f32 v[136:137], v[12:13], v[142:143]
	v_pk_add_f32 v[12:13], v[12:13], v[142:143] neg_lo:[0,1] neg_hi:[0,1]
	s_nop 0
	v_pk_mul_f32 v[142:143], v[12:13], s[18:19]
	s_nop 0
	v_pk_fma_f32 v[12:13], v[12:13], s[30:31], v[142:143] op_sel:[0,0,1] op_sel_hi:[1,0,0] neg_lo:[1,0,0] neg_hi:[1,0,0]
	v_pk_add_f32 v[142:143], v[144:145], v[126:127]
	v_pk_add_f32 v[126:127], v[144:145], v[126:127] neg_lo:[0,1] neg_hi:[0,1]
	v_pk_add_f32 v[144:145], v[158:159], v[128:129]
	v_pk_add_f32 v[128:129], v[158:159], v[128:129] neg_lo:[0,1] neg_hi:[0,1]
	s_nop 0
	v_pk_mul_f32 v[158:159], v[128:129], s[10:11]
	s_nop 0
	v_pk_fma_f32 v[128:129], v[128:129], s[14:15], v[158:159] op_sel:[0,0,1] op_sel_hi:[1,0,0]
	v_pk_add_f32 v[158:159], v[130:131], v[132:133]
	v_pk_add_f32 v[130:131], v[130:131], v[132:133] neg_lo:[0,1] neg_hi:[0,1]
	v_pk_add_f32 v[132:133], v[124:125], v[138:139]
	v_pk_add_f32 v[124:125], v[124:125], v[138:139] neg_lo:[0,1] neg_hi:[0,1]
	s_nop 0
	v_pk_mul_f32 v[138:139], v[124:125], s[10:11]
	s_nop 0
	v_pk_fma_f32 v[124:125], v[124:125], s[14:15], v[138:139] op_sel:[0,0,1] op_sel_hi:[1,0,0] neg_lo:[1,0,0] neg_hi:[1,0,0]
	v_pk_add_f32 v[138:139], v[120:121], v[30:31] op_sel:[0,1] op_sel_hi:[1,0] neg_hi:[0,1]
	v_pk_add_f32 v[30:31], v[120:121], v[30:31] op_sel:[0,1] op_sel_hi:[1,0] neg_lo:[0,1]
	v_pk_add_f32 v[120:121], v[122:123], v[82:83]
	v_pk_add_f32 v[82:83], v[122:123], v[82:83] neg_lo:[0,1] neg_hi:[0,1]
	v_pk_add_f32 v[160:161], v[128:129], v[124:125]
	v_pk_mul_f32 v[122:123], v[82:83], s[10:11]
	v_pk_add_f32 v[124:125], v[128:129], v[124:125] neg_lo:[0,1] neg_hi:[0,1]
	v_pk_fma_f32 v[82:83], v[82:83], s[14:15], v[122:123] op_sel:[0,0,1] op_sel_hi:[1,0,0]
	v_pk_add_f32 v[122:123], v[26:27], v[84:85]
	v_pk_add_f32 v[26:27], v[26:27], v[84:85] neg_lo:[0,1] neg_hi:[0,1]
	v_pk_add_f32 v[84:85], v[28:29], v[118:119]
	v_pk_add_f32 v[28:29], v[28:29], v[118:119] neg_lo:[0,1] neg_hi:[0,1]
	s_nop 0
	v_pk_mul_f32 v[118:119], v[28:29], s[10:11]
	v_pk_add_f32 v[166:167], v[120:121], v[84:85]
	v_pk_fma_f32 v[28:29], v[28:29], s[14:15], v[118:119] op_sel:[0,0,1] op_sel_hi:[1,0,0] neg_lo:[1,0,0] neg_hi:[1,0,0]
	v_pk_add_f32 v[118:119], v[140:141], v[20:21]
	v_pk_add_f32 v[20:21], v[140:141], v[20:21] neg_lo:[0,1] neg_hi:[0,1]
	v_pk_add_f32 v[140:141], v[24:25], v[22:23]
	v_pk_add_f32 v[22:23], v[24:25], v[22:23] neg_lo:[0,1] neg_hi:[0,1]
	v_pk_add_f32 v[84:85], v[120:121], v[84:85] neg_lo:[0,1] neg_hi:[0,1]
	v_pk_mul_f32 v[24:25], v[22:23], s[10:11]
	v_pk_add_f32 v[168:169], v[30:31], v[26:27] op_sel:[0,1] op_sel_hi:[1,0] neg_hi:[0,1]
	v_pk_fma_f32 v[22:23], v[22:23], s[14:15], v[24:25] op_sel:[0,0,1] op_sel_hi:[1,0,0]
	v_pk_add_f32 v[24:25], v[16:17], v[134:135]
	v_pk_add_f32 v[16:17], v[16:17], v[134:135] neg_lo:[0,1] neg_hi:[0,1]
	v_pk_add_f32 v[134:135], v[18:19], v[136:137]
	v_pk_add_f32 v[18:19], v[18:19], v[136:137] neg_lo:[0,1] neg_hi:[0,1]
	s_nop 0
	v_pk_mul_f32 v[136:137], v[18:19], s[10:11]
	v_pk_add_f32 v[26:27], v[30:31], v[26:27] op_sel:[0,1] op_sel_hi:[1,0] neg_lo:[0,1]
	v_pk_fma_f32 v[18:19], v[18:19], s[14:15], v[136:137] op_sel:[0,0,1] op_sel_hi:[1,0,0] neg_lo:[1,0,0] neg_hi:[1,0,0]
	v_pk_add_f32 v[136:137], v[14:15], v[6:7] op_sel:[0,1] op_sel_hi:[1,0] neg_hi:[0,1]
	v_pk_add_f32 v[6:7], v[14:15], v[6:7] op_sel:[0,1] op_sel_hi:[1,0] neg_lo:[0,1]
	v_pk_add_f32 v[14:15], v[0:1], v[8:9]
	v_pk_add_f32 v[0:1], v[0:1], v[8:9] neg_lo:[0,1] neg_hi:[0,1]
	v_pk_add_f32 v[30:31], v[82:83], v[28:29]
	v_pk_mul_f32 v[8:9], v[0:1], s[10:11]
	v_pk_add_f32 v[28:29], v[82:83], v[28:29] neg_lo:[0,1] neg_hi:[0,1]
	v_pk_fma_f32 v[0:1], v[0:1], s[14:15], v[8:9] op_sel:[0,0,1] op_sel_hi:[1,0,0]
	v_pk_add_f32 v[8:9], v[2:3], v[10:11]
	v_pk_add_f32 v[2:3], v[2:3], v[10:11] neg_lo:[0,1] neg_hi:[0,1]
	v_pk_add_f32 v[10:11], v[4:5], v[12:13]
	v_pk_add_f32 v[4:5], v[4:5], v[12:13] neg_lo:[0,1] neg_hi:[0,1]
	s_nop 0
	v_pk_mul_f32 v[12:13], v[4:5], s[10:11]
	v_pk_add_f32 v[170:171], v[118:119], v[24:25]
	v_pk_fma_f32 v[4:5], v[4:5], s[14:15], v[12:13] op_sel:[0,0,1] op_sel_hi:[1,0,0] neg_lo:[1,0,0] neg_hi:[1,0,0]
	v_pk_add_f32 v[12:13], v[142:143], v[158:159]
	v_pk_add_f32 v[142:143], v[142:143], v[158:159] neg_lo:[0,1] neg_hi:[0,1]
	v_pk_add_f32 v[158:159], v[144:145], v[132:133]
	v_pk_add_f32 v[132:133], v[144:145], v[132:133] neg_lo:[0,1] neg_hi:[0,1]
	v_pk_add_f32 v[182:183], v[118:119], v[24:25] neg_lo:[0,1] neg_hi:[0,1]
	v_pk_add_f32 v[184:185], v[140:141], v[134:135]
	v_pk_add_f32 v[24:25], v[140:141], v[134:135] neg_lo:[0,1] neg_hi:[0,1]
	v_pk_add_f32 v[140:141], v[20:21], v[16:17] op_sel:[0,1] op_sel_hi:[1,0] neg_hi:[0,1]
	v_pk_add_f32 v[186:187], v[20:21], v[16:17] op_sel:[0,1] op_sel_hi:[1,0] neg_lo:[0,1]
	v_pk_add_f32 v[16:17], v[22:23], v[18:19] neg_lo:[0,1] neg_hi:[0,1]
	v_pk_add_f32 v[192:193], v[136:137], v[8:9]
	v_pk_add_f32 v[194:195], v[136:137], v[8:9] neg_lo:[0,1] neg_hi:[0,1]
	v_pk_add_f32 v[8:9], v[14:15], v[10:11] neg_lo:[0,1] neg_hi:[0,1]
	v_pk_add_f32 v[198:199], v[6:7], v[2:3] op_sel:[0,1] op_sel_hi:[1,0] neg_hi:[0,1]
	v_pk_add_f32 v[200:201], v[6:7], v[2:3] op_sel:[0,1] op_sel_hi:[1,0] neg_lo:[0,1]
	v_pk_add_f32 v[2:3], v[0:1], v[4:5]
	v_pk_add_f32 v[0:1], v[0:1], v[4:5] neg_lo:[0,1] neg_hi:[0,1]
	v_pk_add_f32 v[144:145], v[126:127], v[130:131] op_sel:[0,1] op_sel_hi:[1,0] neg_hi:[0,1]
	v_pk_add_f32 v[130:131], v[126:127], v[130:131] op_sel:[0,1] op_sel_hi:[1,0] neg_lo:[0,1]
	v_pk_mul_f32 v[162:163], v[124:125], s[22:23]
	v_pk_add_f32 v[164:165], v[138:139], v[122:123]
	v_pk_add_f32 v[138:139], v[138:139], v[122:123] neg_lo:[0,1] neg_hi:[0,1]
	v_pk_mul_f32 v[82:83], v[28:29], s[22:23]
	v_pk_mul_f32 v[134:135], v[24:25], s[22:23]
	v_pk_add_f32 v[188:189], v[22:23], v[18:19]
	v_pk_mul_f32 v[190:191], v[16:17], s[22:23]
	v_pk_add_f32 v[136:137], v[14:15], v[10:11]
	v_pk_mul_f32 v[196:197], v[8:9], s[22:23]
	v_pk_mul_f32 v[202:203], v[0:1], s[22:23]
	v_pk_add_f32 v[28:29], v[12:13], v[158:159]
	v_pk_add_f32 v[128:129], v[12:13], v[158:159] neg_lo:[0,1] neg_hi:[0,1]
	v_pk_add_f32 v[24:25], v[142:143], v[132:133] op_sel:[0,1] op_sel_hi:[1,0] neg_hi:[0,1]
	v_pk_add_f32 v[126:127], v[142:143], v[132:133] op_sel:[0,1] op_sel_hi:[1,0] neg_lo:[0,1]
	v_pk_add_f32 v[20:21], v[144:145], v[160:161]
	v_pk_add_f32 v[124:125], v[144:145], v[160:161] neg_lo:[0,1] neg_hi:[0,1]
	v_pk_add_f32 v[16:17], v[130:131], v[162:163] op_sel:[0,1] op_sel_hi:[1,0]
	v_pk_add_f32 v[122:123], v[130:131], v[162:163] op_sel:[0,1] op_sel_hi:[1,0] neg_lo:[0,1] neg_hi:[0,1]
	v_pk_add_f32 v[12:13], v[164:165], v[166:167]
	v_pk_add_f32 v[120:121], v[164:165], v[166:167] neg_lo:[0,1] neg_hi:[0,1]
	v_pk_add_f32 v[8:9], v[138:139], v[84:85] op_sel:[0,1] op_sel_hi:[1,0] neg_hi:[0,1]
	v_pk_add_f32 v[118:119], v[138:139], v[84:85] op_sel:[0,1] op_sel_hi:[1,0] neg_lo:[0,1]
	v_pk_add_f32 v[4:5], v[168:169], v[30:31]
	v_pk_add_f32 v[84:85], v[168:169], v[30:31] neg_lo:[0,1] neg_hi:[0,1]
	v_pk_add_f32 v[0:1], v[26:27], v[82:83] op_sel:[0,1] op_sel_hi:[1,0]
	v_pk_add_f32 v[82:83], v[26:27], v[82:83] op_sel:[0,1] op_sel_hi:[1,0] neg_lo:[0,1] neg_hi:[0,1]
	v_pk_add_f32 v[30:31], v[170:171], v[184:185]
	v_pk_add_f32 v[144:145], v[170:171], v[184:185] neg_lo:[0,1] neg_hi:[0,1]
	v_pk_add_f32 v[26:27], v[182:183], v[134:135] op_sel:[0,1] op_sel_hi:[1,0]
	v_pk_add_f32 v[142:143], v[182:183], v[134:135] op_sel:[0,1] op_sel_hi:[1,0] neg_lo:[0,1] neg_hi:[0,1]
	v_pk_add_f32 v[22:23], v[140:141], v[188:189]
	v_pk_add_f32 v[140:141], v[140:141], v[188:189] neg_lo:[0,1] neg_hi:[0,1]
	v_pk_add_f32 v[18:19], v[186:187], v[190:191] op_sel:[0,1] op_sel_hi:[1,0]
	v_pk_add_f32 v[138:139], v[186:187], v[190:191] op_sel:[0,1] op_sel_hi:[1,0] neg_lo:[0,1] neg_hi:[0,1]
	v_pk_add_f32 v[14:15], v[192:193], v[136:137]
	v_pk_add_f32 v[136:137], v[192:193], v[136:137] neg_lo:[0,1] neg_hi:[0,1]
	v_pk_add_f32 v[10:11], v[194:195], v[196:197] op_sel:[0,1] op_sel_hi:[1,0]
	v_pk_add_f32 v[134:135], v[194:195], v[196:197] op_sel:[0,1] op_sel_hi:[1,0] neg_lo:[0,1] neg_hi:[0,1]
	v_pk_add_f32 v[6:7], v[198:199], v[2:3]
	v_pk_add_f32 v[132:133], v[198:199], v[2:3] neg_lo:[0,1] neg_hi:[0,1]
	v_pk_add_f32 v[2:3], v[200:201], v[202:203] op_sel:[0,1] op_sel_hi:[1,0]
	v_pk_add_f32 v[130:131], v[200:201], v[202:203] op_sel:[0,1] op_sel_hi:[1,0] neg_lo:[0,1] neg_hi:[0,1]

.LBB0_618:
	v_add_u32_e32 v160, 0x11000, v155
	v_lshlrev_b32_e32 v161, 3, v154
	v_add_u32_e32 v161, 0x2200, v161
	v_add_u32_e32 v162, 0x11100, v156
	v_cmp_ne_u32_e32 vcc, 0, v32
	v_cndmask_b32_e32 v163, 0, v154, vcc
	v_lshlrev_b32_e32 v163, 3, v163
	v_add_u32_e32 v163, 0x11000, v163
	ds_read_b64 v[214:215], v160 offset:0
	ds_read_b64 v[216:217], v163
	ds_read_b64 v[218:219], v122 offset:0
	ds_read_b64 v[220:221], v160 offset:4352
	ds_read_b64 v[222:223], v162 offset:60928
	ds_read_b64 v[224:225], v122 offset:4352
	ds_read_b64 v[226:227], v160 offset:8704
	ds_read_b64 v[228:229], v161 offset:52224
	ds_read_b64 v[230:231], v122 offset:8704
	ds_read_b64 v[232:233], v160 offset:13056
	ds_read_b64 v[234:235], v162 offset:52224
	ds_read_b64 v[236:237], v122 offset:13056
	s_waitcnt lgkmcnt(9)
	v_add_f32_e32 v164, v214, v216
	v_mul_f32_e32 v214, 0.5, v164
	v_sub_f32_e32 v164, v215, v217
	v_mul_f32_e32 v216, 0.5, v164
	v_pk_mul_f32 v[216:217], v[218:219], v[216:217] op_sel:[1,0] op_sel_hi:[0,0]
	v_pk_fma_f32 v[158:159], v[218:219], v[214:215], v[216:217] neg_lo:[0,0,1] neg_hi:[0,0,1]
	v_pk_fma_f32 v[214:215], v[218:219], v[214:215], v[216:217] op_sel_hi:[1,0,1]
	s_nop 0
	v_mov_b32_e32 v159, v215
	v_pk_mul_f32 v[218:219], v[158:159], s[24:25]
	ds_write_b64 v122, v[218:219] offset:0
	s_waitcnt lgkmcnt(7)
	v_add_f32_e32 v164, v220, v222
	v_mul_f32_e32 v220, 0.5, v164
	v_sub_f32_e32 v164, v221, v223
	v_mul_f32_e32 v222, 0.5, v164
	v_pk_mul_f32 v[222:223], v[224:225], v[222:223] op_sel:[1,0] op_sel_hi:[0,0]
	v_pk_fma_f32 v[158:159], v[224:225], v[220:221], v[222:223] neg_lo:[0,0,1] neg_hi:[0,0,1]
	v_pk_fma_f32 v[220:221], v[224:225], v[220:221], v[222:223] op_sel_hi:[1,0,1]
	s_nop 0
	v_mov_b32_e32 v159, v221
	v_pk_mul_f32 v[224:225], v[158:159], s[24:25]
	ds_write_b64 v122, v[224:225] offset:4352
	ds_read_b64 v[182:183], v160 offset:17408
	ds_read_b64 v[184:185], v161 offset:43520
	ds_read_b64 v[186:187], v122 offset:17408
	ds_read_b64 v[188:189], v160 offset:21760
	ds_read_b64 v[190:191], v162 offset:43520
	ds_read_b64 v[192:193], v122 offset:21760
	s_waitcnt lgkmcnt(11)
	v_add_f32_e32 v164, v226, v228
	v_mul_f32_e32 v226, 0.5, v164
	v_sub_f32_e32 v164, v227, v229
	v_mul_f32_e32 v228, 0.5, v164
	v_pk_mul_f32 v[228:229], v[230:231], v[228:229] op_sel:[1,0] op_sel_hi:[0,0]
	v_pk_fma_f32 v[158:159], v[230:231], v[226:227], v[228:229] neg_lo:[0,0,1] neg_hi:[0,0,1]
	v_pk_fma_f32 v[226:227], v[230:231], v[226:227], v[228:229] op_sel_hi:[1,0,1]
	s_nop 0
	v_mov_b32_e32 v159, v227
	v_pk_mul_f32 v[230:231], v[158:159], s[24:25]
	ds_write_b64 v122, v[230:231] offset:8704
	s_waitcnt lgkmcnt(9)
	v_add_f32_e32 v164, v232, v234
	v_mul_f32_e32 v232, 0.5, v164
	v_sub_f32_e32 v164, v233, v235
	v_mul_f32_e32 v234, 0.5, v164
	v_pk_mul_f32 v[234:235], v[236:237], v[234:235] op_sel:[1,0] op_sel_hi:[0,0]
	v_pk_fma_f32 v[158:159], v[236:237], v[232:233], v[234:235] neg_lo:[0,0,1] neg_hi:[0,0,1]
	v_pk_fma_f32 v[232:233], v[236:237], v[232:233], v[234:235] op_sel_hi:[1,0,1]
	s_nop 0
	v_mov_b32_e32 v159, v233
	v_pk_mul_f32 v[236:237], v[158:159], s[24:25]
	ds_write_b64 v122, v[236:237] offset:13056
	ds_read_b64 v[214:215], v160 offset:26112
	ds_read_b64 v[216:217], v161 offset:34816
	ds_read_b64 v[218:219], v122 offset:26112
	ds_read_b64 v[220:221], v160 offset:30464
	ds_read_b64 v[222:223], v162 offset:34816
	ds_read_b64 v[224:225], v122 offset:30464
	s_waitcnt lgkmcnt(11)
	v_add_f32_e32 v164, v182, v184
	v_mul_f32_e32 v182, 0.5, v164
	v_sub_f32_e32 v164, v183, v185
	v_mul_f32_e32 v184, 0.5, v164
	v_pk_mul_f32 v[184:185], v[186:187], v[184:185] op_sel:[1,0] op_sel_hi:[0,0]
	v_pk_fma_f32 v[158:159], v[186:187], v[182:183], v[184:185] neg_lo:[0,0,1] neg_hi:[0,0,1]
	v_pk_fma_f32 v[182:183], v[186:187], v[182:183], v[184:185] op_sel_hi:[1,0,1]
	s_nop 0
	v_mov_b32_e32 v159, v183
	v_pk_mul_f32 v[186:187], v[158:159], s[24:25]
	ds_write_b64 v122, v[186:187] offset:17408
	s_waitcnt lgkmcnt(9)
	v_add_f32_e32 v164, v188, v190
	v_mul_f32_e32 v188, 0.5, v164
	v_sub_f32_e32 v164, v189, v191
	v_mul_f32_e32 v190, 0.5, v164
	v_pk_mul_f32 v[190:191], v[192:193], v[190:191] op_sel:[1,0] op_sel_hi:[0,0]
	v_pk_fma_f32 v[158:159], v[192:193], v[188:189], v[190:191] neg_lo:[0,0,1] neg_hi:[0,0,1]
	v_pk_fma_f32 v[188:189], v[192:193], v[188:189], v[190:191] op_sel_hi:[1,0,1]
	s_nop 0
	v_mov_b32_e32 v159, v189
	v_pk_mul_f32 v[192:193], v[158:159], s[24:25]
	ds_write_b64 v122, v[192:193] offset:21760
	ds_read_b64 v[226:227], v160 offset:34816
	ds_read_b64 v[228:229], v161 offset:26112
	ds_read_b64 v[230:231], v122 offset:34816
	ds_read_b64 v[232:233], v160 offset:39168
	ds_read_b64 v[234:235], v162 offset:26112
	ds_read_b64 v[236:237], v122 offset:39168
	s_waitcnt lgkmcnt(11)
	v_add_f32_e32 v164, v214, v216
	v_mul_f32_e32 v214, 0.5, v164
	v_sub_f32_e32 v164, v215, v217
	v_mul_f32_e32 v216, 0.5, v164
	v_pk_mul_f32 v[216:217], v[218:219], v[216:217] op_sel:[1,0] op_sel_hi:[0,0]
	v_pk_fma_f32 v[158:159], v[218:219], v[214:215], v[216:217] neg_lo:[0,0,1] neg_hi:[0,0,1]
	v_pk_fma_f32 v[214:215], v[218:219], v[214:215], v[216:217] op_sel_hi:[1,0,1]
	s_nop 0
	v_mov_b32_e32 v159, v215
	v_pk_mul_f32 v[218:219], v[158:159], s[24:25]
	ds_write_b64 v122, v[218:219] offset:26112
	s_waitcnt lgkmcnt(9)
	v_add_f32_e32 v164, v220, v222
	v_mul_f32_e32 v220, 0.5, v164
	v_sub_f32_e32 v164, v221, v223
	v_mul_f32_e32 v222, 0.5, v164
	v_pk_mul_f32 v[222:223], v[224:225], v[222:223] op_sel:[1,0] op_sel_hi:[0,0]
	v_pk_fma_f32 v[158:159], v[224:225], v[220:221], v[222:223] neg_lo:[0,0,1] neg_hi:[0,0,1]
	v_pk_fma_f32 v[220:221], v[224:225], v[220:221], v[222:223] op_sel_hi:[1,0,1]
	s_nop 0
	v_mov_b32_e32 v159, v221
	v_pk_mul_f32 v[224:225], v[158:159], s[24:25]
	ds_write_b64 v122, v[224:225] offset:30464
	ds_read_b64 v[182:183], v160 offset:43520
	ds_read_b64 v[184:185], v161 offset:17408
	ds_read_b64 v[186:187], v122 offset:43520
	ds_read_b64 v[188:189], v160 offset:47872
	ds_read_b64 v[190:191], v162 offset:17408
	ds_read_b64 v[192:193], v122 offset:47872
	s_waitcnt lgkmcnt(11)
	v_add_f32_e32 v164, v226, v228
	v_mul_f32_e32 v226, 0.5, v164
	v_sub_f32_e32 v164, v227, v229
	v_mul_f32_e32 v228, 0.5, v164
	v_pk_mul_f32 v[228:229], v[230:231], v[228:229] op_sel:[1,0] op_sel_hi:[0,0]
	v_pk_fma_f32 v[158:159], v[230:231], v[226:227], v[228:229] neg_lo:[0,0,1] neg_hi:[0,0,1]
	v_pk_fma_f32 v[226:227], v[230:231], v[226:227], v[228:229] op_sel_hi:[1,0,1]
	s_nop 0
	v_mov_b32_e32 v159, v227
	v_pk_mul_f32 v[230:231], v[158:159], s[24:25]
	ds_write_b64 v122, v[230:231] offset:34816
	s_waitcnt lgkmcnt(9)
	v_add_f32_e32 v164, v232, v234
	v_mul_f32_e32 v232, 0.5, v164
	v_sub_f32_e32 v164, v233, v235
	v_mul_f32_e32 v234, 0.5, v164
	v_pk_mul_f32 v[234:235], v[236:237], v[234:235] op_sel:[1,0] op_sel_hi:[0,0]
	v_pk_fma_f32 v[158:159], v[236:237], v[232:233], v[234:235] neg_lo:[0,0,1] neg_hi:[0,0,1]
	v_pk_fma_f32 v[232:233], v[236:237], v[232:233], v[234:235] op_sel_hi:[1,0,1]
	s_nop 0
	v_mov_b32_e32 v159, v233
	v_pk_mul_f32 v[236:237], v[158:159], s[24:25]
	ds_write_b64 v122, v[236:237] offset:39168
	ds_read_b64 v[214:215], v160 offset:52224
	ds_read_b64 v[216:217], v161 offset:8704
	ds_read_b64 v[218:219], v122 offset:52224
	ds_read_b64 v[220:221], v160 offset:56576
	ds_read_b64 v[222:223], v162 offset:8704
	ds_read_b64 v[224:225], v122 offset:56576
	s_waitcnt lgkmcnt(11)
	v_add_f32_e32 v164, v182, v184
	v_mul_f32_e32 v182, 0.5, v164
	v_sub_f32_e32 v164, v183, v185
	v_mul_f32_e32 v184, 0.5, v164
	v_pk_mul_f32 v[184:185], v[186:187], v[184:185] op_sel:[1,0] op_sel_hi:[0,0]
	v_pk_fma_f32 v[158:159], v[186:187], v[182:183], v[184:185] neg_lo:[0,0,1] neg_hi:[0,0,1]
	v_pk_fma_f32 v[182:183], v[186:187], v[182:183], v[184:185] op_sel_hi:[1,0,1]
	s_nop 0
	v_mov_b32_e32 v159, v183
	v_pk_mul_f32 v[186:187], v[158:159], s[24:25]
	ds_write_b64 v122, v[186:187] offset:43520
	s_waitcnt lgkmcnt(9)
	v_add_f32_e32 v164, v188, v190
	v_mul_f32_e32 v188, 0.5, v164
	v_sub_f32_e32 v164, v189, v191
	v_mul_f32_e32 v190, 0.5, v164
	v_pk_mul_f32 v[190:191], v[192:193], v[190:191] op_sel:[1,0] op_sel_hi:[0,0]
	v_pk_fma_f32 v[158:159], v[192:193], v[188:189], v[190:191] neg_lo:[0,0,1] neg_hi:[0,0,1]
	v_pk_fma_f32 v[188:189], v[192:193], v[188:189], v[190:191] op_sel_hi:[1,0,1]
	s_nop 0
	v_mov_b32_e32 v159, v189
	v_pk_mul_f32 v[192:193], v[158:159], s[24:25]
	ds_write_b64 v122, v[192:193] offset:47872
	ds_read_b64 v[226:227], v160 offset:60928
	ds_read_b64 v[228:229], v161 offset:0
	ds_read_b64 v[230:231], v122 offset:60928
	ds_read_b64 v[232:233], v160 offset:65280
	ds_read_b64 v[234:235], v162 offset:0
	ds_read_b64 v[236:237], v122 offset:65280
	s_waitcnt lgkmcnt(11)
	v_add_f32_e32 v164, v214, v216
	v_mul_f32_e32 v214, 0.5, v164
	v_sub_f32_e32 v164, v215, v217
	v_mul_f32_e32 v216, 0.5, v164
	v_pk_mul_f32 v[216:217], v[218:219], v[216:217] op_sel:[1,0] op_sel_hi:[0,0]
	v_pk_fma_f32 v[158:159], v[218:219], v[214:215], v[216:217] neg_lo:[0,0,1] neg_hi:[0,0,1]
	v_pk_fma_f32 v[214:215], v[218:219], v[214:215], v[216:217] op_sel_hi:[1,0,1]
	s_nop 0
	v_mov_b32_e32 v159, v215
	v_pk_mul_f32 v[218:219], v[158:159], s[24:25]
	ds_write_b64 v122, v[218:219] offset:52224
	s_waitcnt lgkmcnt(9)
	v_add_f32_e32 v164, v220, v222
	v_mul_f32_e32 v220, 0.5, v164
	v_sub_f32_e32 v164, v221, v223
	v_mul_f32_e32 v222, 0.5, v164
	v_pk_mul_f32 v[222:223], v[224:225], v[222:223] op_sel:[1,0] op_sel_hi:[0,0]
	v_pk_fma_f32 v[158:159], v[224:225], v[220:221], v[222:223] neg_lo:[0,0,1] neg_hi:[0,0,1]
	v_pk_fma_f32 v[220:221], v[224:225], v[220:221], v[222:223] op_sel_hi:[1,0,1]
	s_nop 0
	v_mov_b32_e32 v159, v221
	v_pk_mul_f32 v[224:225], v[158:159], s[24:25]
	ds_write_b64 v122, v[224:225] offset:56576
	s_waitcnt lgkmcnt(5)
	v_add_f32_e32 v164, v226, v228
	v_mul_f32_e32 v226, 0.5, v164
	v_sub_f32_e32 v164, v227, v229
	v_mul_f32_e32 v228, 0.5, v164
	v_pk_mul_f32 v[228:229], v[230:231], v[228:229] op_sel:[1,0] op_sel_hi:[0,0]
	v_pk_fma_f32 v[158:159], v[230:231], v[226:227], v[228:229] neg_lo:[0,0,1] neg_hi:[0,0,1]
	v_pk_fma_f32 v[226:227], v[230:231], v[226:227], v[228:229] op_sel_hi:[1,0,1]
	s_nop 0
	v_mov_b32_e32 v159, v227
	v_pk_mul_f32 v[230:231], v[158:159], s[24:25]
	ds_write_b64 v122, v[230:231] offset:60928
	s_waitcnt lgkmcnt(3)
	v_add_f32_e32 v164, v232, v234
	v_mul_f32_e32 v232, 0.5, v164
	v_sub_f32_e32 v164, v233, v235
	v_mul_f32_e32 v234, 0.5, v164
	v_pk_mul_f32 v[234:235], v[236:237], v[234:235] op_sel:[1,0] op_sel_hi:[0,0]
	v_pk_fma_f32 v[158:159], v[236:237], v[232:233], v[234:235] neg_lo:[0,0,1] neg_hi:[0,0,1]
	v_pk_fma_f32 v[232:233], v[236:237], v[232:233], v[234:235] op_sel_hi:[1,0,1]
	s_nop 0
	v_mov_b32_e32 v159, v233
	v_pk_mul_f32 v[236:237], v[158:159], s[24:25]
	ds_write_b64 v122, v[236:237] offset:65280
	s_mov_b32 s4, 16
	s_cmp_lg_u32 s4, 16
	s_waitcnt lgkmcnt(0)
	s_barrier
	s_and_saveexec_b64 s[28:29], s[40:41]
	s_cbranch_execz .LBB0_621
	ds_read_b64 v[0:1], v153
	ds_read_b64 v[2:3], v153 offset:2176
	ds_read_b64 v[4:5], v153 offset:4352
	ds_read_b64 v[6:7], v153 offset:6528
	ds_read_b64 v[8:9], v153 offset:8704
	ds_read_b64 v[10:11], v153 offset:10880
	ds_read_b64 v[12:13], v153 offset:13056
	ds_read_b64 v[14:15], v153 offset:15232
	ds_read_b64 v[16:17], v153 offset:17408
	ds_read_b64 v[18:19], v153 offset:19584
	ds_read_b64 v[20:21], v153 offset:21760
	ds_read_b64 v[22:23], v153 offset:23936
	ds_read_b64 v[24:25], v153 offset:26112
	ds_read_b64 v[26:27], v153 offset:28288
	ds_read_b64 v[28:29], v153 offset:30464
	ds_read_b64 v[30:31], v153 offset:32640
	ds_read_b64 v[86:87], v153 offset:34816
	ds_read_b64 v[92:93], v153 offset:41344
	ds_read_b64 v[94:95], v153 offset:43520
	ds_read_b64 v[96:97], v153 offset:45696
	ds_read_b64 v[98:99], v153 offset:47872
	ds_read_b64 v[100:101], v153 offset:50048
	ds_read_b64 v[102:103], v153 offset:52224
	ds_read_b64 v[104:105], v153 offset:54400
	ds_read_b64 v[106:107], v153 offset:56576
	ds_read_b64 v[108:109], v153 offset:58752
	ds_read_b64 v[110:111], v153 offset:60928
	ds_read_b64 v[112:113], v153 offset:63104
	ds_read_b64 v[114:115], v153 offset:65280
	ds_read_b64 v[116:117], v153 offset:36992
	ds_read_b64 v[118:119], v153 offset:39168
	ds_read_b64 v[120:121], v33
	s_waitcnt lgkmcnt(14)
	v_pk_add_f32 v[124:125], v[0:1], v[86:87]
	v_pk_add_f32 v[0:1], v[0:1], v[86:87] neg_lo:[0,1] neg_hi:[0,1]
	s_waitcnt lgkmcnt(2)
	v_pk_add_f32 v[86:87], v[2:3], v[116:117]
	v_pk_add_f32 v[2:3], v[2:3], v[116:117] neg_lo:[0,1] neg_hi:[0,1]
	s_mov_b32 s11, s14
	v_pk_mul_f32 v[116:117], v[2:3], s[16:17]
	s_mov_b32 s13, s86
	v_pk_fma_f32 v[2:3], v[2:3], s[6:7], v[116:117] op_sel:[0,0,1] op_sel_hi:[1,0,0]
	s_waitcnt lgkmcnt(1)
	v_pk_add_f32 v[116:117], v[4:5], v[118:119]
	v_pk_add_f32 v[4:5], v[4:5], v[118:119] neg_lo:[0,1] neg_hi:[0,1]
	s_mov_b32 s4, s21
	v_pk_mul_f32 v[118:119], v[4:5], s[18:19]
	s_mov_b32 s35, s30
	v_pk_fma_f32 v[4:5], v[4:5], s[30:31], v[118:119] op_sel:[0,0,1] op_sel_hi:[1,0,0]
	v_pk_add_f32 v[118:119], v[6:7], v[92:93]
	v_pk_add_f32 v[6:7], v[6:7], v[92:93] neg_lo:[0,1] neg_hi:[0,1]
	s_mov_b32 s8, s19
	v_pk_mul_f32 v[92:93], v[6:7], s[20:21]
	s_mov_b32 s77, s6
	v_pk_fma_f32 v[6:7], v[6:7], s[86:87], v[92:93] op_sel:[0,0,1] op_sel_hi:[1,0,0]
	v_pk_add_f32 v[92:93], v[8:9], v[94:95]
	v_pk_add_f32 v[8:9], v[8:9], v[94:95] neg_lo:[0,1] neg_hi:[0,1]
	s_mov_b32 s26, s17
	v_pk_mul_f32 v[94:95], v[8:9], s[10:11]
	s_nop 0
	v_pk_fma_f32 v[8:9], v[8:9], s[14:15], v[94:95] op_sel:[0,0,1] op_sel_hi:[1,0,0]
	v_pk_add_f32 v[94:95], v[10:11], v[96:97]
	v_pk_add_f32 v[10:11], v[10:11], v[96:97] neg_lo:[0,1] neg_hi:[0,1]
	s_nop 0
	v_pk_mul_f32 v[96:97], v[10:11], s[12:13]
	s_nop 0
	v_pk_fma_f32 v[10:11], v[10:11], s[4:5], v[96:97] op_sel:[0,0,1] op_sel_hi:[1,0,0]
	v_pk_add_f32 v[96:97], v[12:13], v[98:99]
	v_pk_add_f32 v[12:13], v[12:13], v[98:99] neg_lo:[0,1] neg_hi:[0,1]
	s_nop 0
	v_pk_mul_f32 v[98:99], v[12:13], s[34:35]
	s_nop 0
	v_pk_fma_f32 v[12:13], v[12:13], s[8:9], v[98:99] op_sel:[0,0,1] op_sel_hi:[1,0,0]
	v_pk_add_f32 v[98:99], v[14:15], v[100:101]
	v_pk_add_f32 v[14:15], v[14:15], v[100:101] neg_lo:[0,1] neg_hi:[0,1]
	s_nop 0
	v_pk_mul_f32 v[100:101], v[14:15], s[76:77]
	s_nop 0
	v_pk_fma_f32 v[14:15], v[14:15], s[26:27], v[100:101] op_sel:[0,0,1] op_sel_hi:[1,0,0]
	v_pk_add_f32 v[100:101], v[16:17], v[102:103]
	v_pk_add_f32 v[16:17], v[16:17], v[102:103] neg_lo:[0,1] neg_hi:[0,1]
	v_pk_add_f32 v[102:103], v[18:19], v[104:105]
	v_pk_add_f32 v[18:19], v[18:19], v[104:105] neg_lo:[0,1] neg_hi:[0,1]
	s_nop 0
	v_pk_mul_f32 v[104:105], v[18:19], s[76:77]
	s_nop 0
	v_pk_fma_f32 v[18:19], v[18:19], s[26:27], v[104:105] op_sel:[0,0,1] op_sel_hi:[1,0,0] neg_lo:[1,0,0] neg_hi:[1,0,0]
	v_pk_add_f32 v[104:105], v[20:21], v[106:107]
	v_pk_add_f32 v[20:21], v[20:21], v[106:107] neg_lo:[0,1] neg_hi:[0,1]
	s_nop 0
	v_pk_mul_f32 v[106:107], v[20:21], s[34:35]
	s_nop 0
	v_pk_fma_f32 v[20:21], v[20:21], s[8:9], v[106:107] op_sel:[0,0,1] op_sel_hi:[1,0,0] neg_lo:[1,0,0] neg_hi:[1,0,0]
	v_pk_add_f32 v[106:107], v[22:23], v[108:109]
	v_pk_add_f32 v[22:23], v[22:23], v[108:109] neg_lo:[0,1] neg_hi:[0,1]
	s_nop 0
	v_pk_mul_f32 v[108:109], v[22:23], s[12:13]
	s_nop 0
	v_pk_fma_f32 v[22:23], v[22:23], s[4:5], v[108:109] op_sel:[0,0,1] op_sel_hi:[1,0,0] neg_lo:[1,0,0] neg_hi:[1,0,0]
	v_pk_add_f32 v[108:109], v[24:25], v[110:111]
	v_pk_add_f32 v[24:25], v[24:25], v[110:111] neg_lo:[0,1] neg_hi:[0,1]
	s_nop 0
	v_pk_mul_f32 v[110:111], v[24:25], s[10:11]
	s_nop 0
	v_pk_fma_f32 v[24:25], v[24:25], s[14:15], v[110:111] op_sel:[0,0,1] op_sel_hi:[1,0,0] neg_lo:[1,0,0] neg_hi:[1,0,0]
	v_pk_add_f32 v[110:111], v[26:27], v[112:113]
	v_pk_add_f32 v[26:27], v[26:27], v[112:113] neg_lo:[0,1] neg_hi:[0,1]
	s_nop 0
	v_pk_mul_f32 v[112:113], v[26:27], s[20:21]
	s_nop 0
	v_pk_fma_f32 v[26:27], v[26:27], s[86:87], v[112:113] op_sel:[0,0,1] op_sel_hi:[1,0,0] neg_lo:[1,0,0] neg_hi:[1,0,0]
	v_pk_add_f32 v[112:113], v[28:29], v[114:115]
	v_pk_add_f32 v[28:29], v[28:29], v[114:115] neg_lo:[0,1] neg_hi:[0,1]
	s_nop 0
	v_pk_mul_f32 v[114:115], v[28:29], s[18:19]
	s_nop 0
	v_pk_fma_f32 v[28:29], v[28:29], s[30:31], v[114:115] op_sel:[0,0,1] op_sel_hi:[1,0,0] neg_lo:[1,0,0] neg_hi:[1,0,0]
	s_waitcnt lgkmcnt(0)
	v_pk_add_f32 v[114:115], v[30:31], v[120:121]
	v_pk_add_f32 v[30:31], v[30:31], v[120:121] neg_lo:[0,1] neg_hi:[0,1]
	s_nop 0
	v_pk_mul_f32 v[120:121], v[30:31], s[16:17]
	s_nop 0
	v_pk_fma_f32 v[30:31], v[30:31], s[6:7], v[120:121] op_sel:[0,0,1] op_sel_hi:[1,0,0] neg_lo:[1,0,0] neg_hi:[1,0,0]
	v_pk_add_f32 v[120:121], v[124:125], v[100:101]
	v_pk_add_f32 v[100:101], v[124:125], v[100:101] neg_lo:[0,1] neg_hi:[0,1]
	v_pk_add_f32 v[124:125], v[86:87], v[102:103]
	v_pk_add_f32 v[86:87], v[86:87], v[102:103] neg_lo:[0,1] neg_hi:[0,1]
	s_nop 0
	v_pk_mul_f32 v[102:103], v[86:87], s[18:19]
	s_nop 0
	v_pk_fma_f32 v[86:87], v[86:87], s[30:31], v[102:103] op_sel:[0,0,1] op_sel_hi:[1,0,0]
	v_pk_add_f32 v[102:103], v[116:117], v[104:105]
	v_pk_add_f32 v[104:105], v[116:117], v[104:105] neg_lo:[0,1] neg_hi:[0,1]
	s_nop 0
	v_pk_mul_f32 v[116:117], v[104:105], s[10:11]
	s_nop 0
	v_pk_fma_f32 v[104:105], v[104:105], s[14:15], v[116:117] op_sel:[0,0,1] op_sel_hi:[1,0,0]
	v_pk_add_f32 v[116:117], v[118:119], v[106:107]
	v_pk_add_f32 v[106:107], v[118:119], v[106:107] neg_lo:[0,1] neg_hi:[0,1]
	s_nop 0
	v_pk_mul_f32 v[118:119], v[106:107], s[34:35]
	s_nop 0
	v_pk_fma_f32 v[106:107], v[106:107], s[8:9], v[118:119] op_sel:[0,0,1] op_sel_hi:[1,0,0]
	v_pk_add_f32 v[118:119], v[92:93], v[108:109]
	v_pk_add_f32 v[92:93], v[92:93], v[108:109] neg_lo:[0,1] neg_hi:[0,1]
	v_pk_add_f32 v[108:109], v[94:95], v[110:111]
	v_pk_add_f32 v[94:95], v[94:95], v[110:111] neg_lo:[0,1] neg_hi:[0,1]
	s_nop 0
	v_pk_mul_f32 v[110:111], v[94:95], s[34:35]
	s_nop 0
	v_pk_fma_f32 v[94:95], v[94:95], s[8:9], v[110:111] op_sel:[0,0,1] op_sel_hi:[1,0,0] neg_lo:[1,0,0] neg_hi:[1,0,0]
	v_pk_add_f32 v[110:111], v[96:97], v[112:113]
	v_pk_add_f32 v[96:97], v[96:97], v[112:113] neg_lo:[0,1] neg_hi:[0,1]
	s_nop 0
	v_pk_mul_f32 v[112:113], v[96:97], s[10:11]
	s_nop 0
	v_pk_fma_f32 v[96:97], v[96:97], s[14:15], v[112:113] op_sel:[0,0,1] op_sel_hi:[1,0,0] neg_lo:[1,0,0] neg_hi:[1,0,0]
	v_pk_add_f32 v[112:113], v[98:99], v[114:115]
	v_pk_add_f32 v[98:99], v[98:99], v[114:115] neg_lo:[0,1] neg_hi:[0,1]
	s_nop 0
	v_pk_mul_f32 v[114:115], v[98:99], s[18:19]
	s_nop 0
	v_pk_fma_f32 v[98:99], v[98:99], s[30:31], v[114:115] op_sel:[0,0,1] op_sel_hi:[1,0,0] neg_lo:[1,0,0] neg_hi:[1,0,0]
	v_pk_add_f32 v[114:115], v[0:1], v[16:17] op_sel:[0,1] op_sel_hi:[1,0] neg_hi:[0,1]
	v_pk_add_f32 v[0:1], v[0:1], v[16:17] op_sel:[0,1] op_sel_hi:[1,0] neg_lo:[0,1]
	v_pk_add_f32 v[16:17], v[2:3], v[18:19]
	v_pk_add_f32 v[2:3], v[2:3], v[18:19] neg_lo:[0,1] neg_hi:[0,1]
	s_nop 0
	v_pk_mul_f32 v[18:19], v[2:3], s[18:19]
	s_nop 0
	v_pk_fma_f32 v[2:3], v[2:3], s[30:31], v[18:19] op_sel:[0,0,1] op_sel_hi:[1,0,0]
	v_pk_add_f32 v[18:19], v[4:5], v[20:21]
	v_pk_add_f32 v[4:5], v[4:5], v[20:21] neg_lo:[0,1] neg_hi:[0,1]
	s_nop 0
	v_pk_mul_f32 v[20:21], v[4:5], s[10:11]
	s_nop 0
	v_pk_fma_f32 v[4:5], v[4:5], s[14:15], v[20:21] op_sel:[0,0,1] op_sel_hi:[1,0,0]
	v_pk_add_f32 v[20:21], v[6:7], v[22:23]
	v_pk_add_f32 v[6:7], v[6:7], v[22:23] neg_lo:[0,1] neg_hi:[0,1]
	s_nop 0
	v_pk_mul_f32 v[22:23], v[6:7], s[34:35]
	s_nop 0
	v_pk_fma_f32 v[6:7], v[6:7], s[8:9], v[22:23] op_sel:[0,0,1] op_sel_hi:[1,0,0]
	v_pk_add_f32 v[22:23], v[8:9], v[24:25]
	v_pk_add_f32 v[8:9], v[8:9], v[24:25] neg_lo:[0,1] neg_hi:[0,1]
	v_pk_add_f32 v[24:25], v[10:11], v[26:27]
	v_pk_add_f32 v[10:11], v[10:11], v[26:27] neg_lo:[0,1] neg_hi:[0,1]
	s_nop 0
	v_pk_mul_f32 v[26:27], v[10:11], s[34:35]
	s_nop 0
	v_pk_fma_f32 v[10:11], v[10:11], s[8:9], v[26:27] op_sel:[0,0,1] op_sel_hi:[1,0,0] neg_lo:[1,0,0] neg_hi:[1,0,0]
	v_pk_add_f32 v[26:27], v[12:13], v[28:29]
	v_pk_add_f32 v[12:13], v[12:13], v[28:29] neg_lo:[0,1] neg_hi:[0,1]
	s_nop 0
	v_pk_mul_f32 v[28:29], v[12:13], s[10:11]
	s_nop 0
	v_pk_fma_f32 v[12:13], v[12:13], s[14:15], v[28:29] op_sel:[0,0,1] op_sel_hi:[1,0,0] neg_lo:[1,0,0] neg_hi:[1,0,0]
	v_pk_add_f32 v[28:29], v[14:15], v[30:31]
	v_pk_add_f32 v[14:15], v[14:15], v[30:31] neg_lo:[0,1] neg_hi:[0,1]
	s_nop 0
	v_pk_mul_f32 v[30:31], v[14:15], s[18:19]
	s_nop 0
	v_pk_fma_f32 v[14:15], v[14:15], s[30:31], v[30:31] op_sel:[0,0,1] op_sel_hi:[1,0,0] neg_lo:[1,0,0] neg_hi:[1,0,0]
	v_pk_add_f32 v[30:31], v[120:121], v[118:119]
	v_pk_add_f32 v[118:119], v[120:121], v[118:119] neg_lo:[0,1] neg_hi:[0,1]
	v_pk_add_f32 v[120:121], v[124:125], v[108:109]
	v_pk_add_f32 v[108:109], v[124:125], v[108:109] neg_lo:[0,1] neg_hi:[0,1]
	s_nop 0
	v_pk_mul_f32 v[124:125], v[108:109], s[10:11]
	s_nop 0
	v_pk_fma_f32 v[108:109], v[108:109], s[14:15], v[124:125] op_sel:[0,0,1] op_sel_hi:[1,0,0]
	v_pk_add_f32 v[124:125], v[102:103], v[110:111]
	v_pk_add_f32 v[102:103], v[102:103], v[110:111] neg_lo:[0,1] neg_hi:[0,1]
	v_pk_add_f32 v[110:111], v[116:117], v[112:113]
	v_pk_add_f32 v[112:113], v[116:117], v[112:113] neg_lo:[0,1] neg_hi:[0,1]
	s_nop 0
	v_pk_mul_f32 v[116:117], v[112:113], s[10:11]
	s_nop 0
	v_pk_fma_f32 v[112:113], v[112:113], s[14:15], v[116:117] op_sel:[0,0,1] op_sel_hi:[1,0,0] neg_lo:[1,0,0] neg_hi:[1,0,0]
	v_pk_add_f32 v[116:117], v[100:101], v[92:93] op_sel:[0,1] op_sel_hi:[1,0] neg_hi:[0,1]
	v_pk_add_f32 v[92:93], v[100:101], v[92:93] op_sel:[0,1] op_sel_hi:[1,0] neg_lo:[0,1]
	v_pk_add_f32 v[100:101], v[86:87], v[94:95]
	v_pk_add_f32 v[86:87], v[86:87], v[94:95] neg_lo:[0,1] neg_hi:[0,1]
	v_pk_add_f32 v[126:127], v[108:109], v[112:113]
	v_pk_mul_f32 v[94:95], v[86:87], s[10:11]
	s_nop 0
	v_pk_fma_f32 v[86:87], v[86:87], s[14:15], v[94:95] op_sel:[0,0,1] op_sel_hi:[1,0,0]
	v_pk_add_f32 v[94:95], v[104:105], v[96:97]
	v_pk_add_f32 v[96:97], v[104:105], v[96:97] neg_lo:[0,1] neg_hi:[0,1]
	v_pk_add_f32 v[104:105], v[106:107], v[98:99]
	v_pk_add_f32 v[98:99], v[106:107], v[98:99] neg_lo:[0,1] neg_hi:[0,1]
	s_nop 0
	v_pk_mul_f32 v[106:107], v[98:99], s[10:11]
	v_pk_add_f32 v[130:131], v[92:93], v[96:97] op_sel:[0,1] op_sel_hi:[1,0] neg_hi:[0,1]
	v_pk_fma_f32 v[98:99], v[98:99], s[14:15], v[106:107] op_sel:[0,0,1] op_sel_hi:[1,0,0] neg_lo:[1,0,0] neg_hi:[1,0,0]
	v_pk_add_f32 v[106:107], v[114:115], v[22:23]
	v_pk_add_f32 v[22:23], v[114:115], v[22:23] neg_lo:[0,1] neg_hi:[0,1]
	v_pk_add_f32 v[114:115], v[16:17], v[24:25]
	v_pk_add_f32 v[16:17], v[16:17], v[24:25] neg_lo:[0,1] neg_hi:[0,1]
	v_pk_add_f32 v[132:133], v[92:93], v[96:97] op_sel:[0,1] op_sel_hi:[1,0] neg_lo:[0,1]
	v_pk_mul_f32 v[24:25], v[16:17], s[10:11]
	v_pk_add_f32 v[92:93], v[86:87], v[98:99]
	v_pk_fma_f32 v[16:17], v[16:17], s[14:15], v[24:25] op_sel:[0,0,1] op_sel_hi:[1,0,0]
	v_pk_add_f32 v[24:25], v[18:19], v[26:27]
	v_pk_add_f32 v[18:19], v[18:19], v[26:27] neg_lo:[0,1] neg_hi:[0,1]
	v_pk_add_f32 v[26:27], v[20:21], v[28:29]
	v_pk_add_f32 v[20:21], v[20:21], v[28:29] neg_lo:[0,1] neg_hi:[0,1]
	s_nop 0
	v_pk_mul_f32 v[28:29], v[20:21], s[10:11]
	v_pk_add_f32 v[86:87], v[86:87], v[98:99] neg_lo:[0,1] neg_hi:[0,1]
	v_pk_fma_f32 v[20:21], v[20:21], s[14:15], v[28:29] op_sel:[0,0,1] op_sel_hi:[1,0,0] neg_lo:[1,0,0] neg_hi:[1,0,0]
	v_pk_add_f32 v[28:29], v[0:1], v[8:9] op_sel:[0,1] op_sel_hi:[1,0] neg_hi:[0,1]
	v_pk_add_f32 v[0:1], v[0:1], v[8:9] op_sel:[0,1] op_sel_hi:[1,0] neg_lo:[0,1]
	v_pk_add_f32 v[8:9], v[2:3], v[10:11]
	v_pk_add_f32 v[2:3], v[2:3], v[10:11] neg_lo:[0,1] neg_hi:[0,1]
	v_pk_add_f32 v[134:135], v[106:107], v[24:25]
	v_pk_mul_f32 v[10:11], v[2:3], s[10:11]
	v_pk_add_f32 v[106:107], v[106:107], v[24:25] neg_lo:[0,1] neg_hi:[0,1]
	v_pk_fma_f32 v[2:3], v[2:3], s[14:15], v[10:11] op_sel:[0,0,1] op_sel_hi:[1,0,0]
	v_pk_add_f32 v[10:11], v[4:5], v[12:13]
	v_pk_add_f32 v[4:5], v[4:5], v[12:13] neg_lo:[0,1] neg_hi:[0,1]
	v_pk_add_f32 v[12:13], v[6:7], v[14:15]
	v_pk_add_f32 v[6:7], v[6:7], v[14:15] neg_lo:[0,1] neg_hi:[0,1]
	s_nop 0
	v_pk_mul_f32 v[14:15], v[6:7], s[10:11]
	v_pk_add_f32 v[24:25], v[114:115], v[26:27] neg_lo:[0,1] neg_hi:[0,1]
	v_pk_fma_f32 v[6:7], v[6:7], s[14:15], v[14:15] op_sel:[0,0,1] op_sel_hi:[1,0,0] neg_lo:[1,0,0] neg_hi:[1,0,0]
	v_pk_add_f32 v[14:15], v[30:31], v[124:125]
	v_pk_add_f32 v[30:31], v[30:31], v[124:125] neg_lo:[0,1] neg_hi:[0,1]
	v_pk_add_f32 v[124:125], v[120:121], v[110:111]
	v_pk_add_f32 v[110:111], v[120:121], v[110:111] neg_lo:[0,1] neg_hi:[0,1]
	v_pk_add_f32 v[120:121], v[118:119], v[102:103] op_sel:[0,1] op_sel_hi:[1,0] neg_hi:[0,1]
	v_pk_add_f32 v[118:119], v[118:119], v[102:103] op_sel:[0,1] op_sel_hi:[1,0] neg_lo:[0,1]
	v_pk_add_f32 v[102:103], v[108:109], v[112:113] neg_lo:[0,1] neg_hi:[0,1]
	v_pk_add_f32 v[112:113], v[116:117], v[94:95]
	v_pk_add_f32 v[94:95], v[116:117], v[94:95] neg_lo:[0,1] neg_hi:[0,1]
	v_pk_add_f32 v[116:117], v[100:101], v[104:105]
	v_pk_add_f32 v[100:101], v[100:101], v[104:105] neg_lo:[0,1] neg_hi:[0,1]
	v_pk_add_f32 v[138:139], v[22:23], v[18:19] op_sel:[0,1] op_sel_hi:[1,0] neg_hi:[0,1]
	v_pk_add_f32 v[140:141], v[22:23], v[18:19] op_sel:[0,1] op_sel_hi:[1,0] neg_lo:[0,1]
	v_pk_add_f32 v[18:19], v[16:17], v[20:21]
	v_pk_add_f32 v[16:17], v[16:17], v[20:21] neg_lo:[0,1] neg_hi:[0,1]
	v_pk_add_f32 v[144:145], v[28:29], v[10:11]
	v_pk_add_f32 v[158:159], v[28:29], v[10:11] neg_lo:[0,1] neg_hi:[0,1]
	v_pk_add_f32 v[10:11], v[8:9], v[12:13]
	v_pk_add_f32 v[8:9], v[8:9], v[12:13] neg_lo:[0,1] neg_hi:[0,1]
	v_pk_add_f32 v[162:163], v[0:1], v[4:5] op_sel:[0,1] op_sel_hi:[1,0] neg_hi:[0,1]
	v_pk_add_f32 v[164:165], v[0:1], v[4:5] op_sel:[0,1] op_sel_hi:[1,0] neg_lo:[0,1]
	v_pk_add_f32 v[0:1], v[2:3], v[6:7] neg_lo:[0,1] neg_hi:[0,1]
	v_pk_mul_f32 v[108:109], v[102:103], s[22:23]
	v_pk_mul_f32 v[128:129], v[100:101], s[22:23]
	v_pk_add_f32 v[136:137], v[114:115], v[26:27]
	v_pk_mul_f32 v[114:115], v[24:25], s[22:23]
	v_pk_mul_f32 v[142:143], v[16:17], s[22:23]
	v_pk_mul_f32 v[160:161], v[8:9], s[22:23]
	v_pk_add_f32 v[166:167], v[2:3], v[6:7]
	v_pk_mul_f32 v[168:169], v[0:1], s[22:23]
	v_pk_add_f32 v[28:29], v[14:15], v[124:125]
	v_pk_add_f32 v[104:105], v[14:15], v[124:125] neg_lo:[0,1] neg_hi:[0,1]
	v_pk_add_f32 v[24:25], v[30:31], v[110:111] op_sel:[0,1] op_sel_hi:[1,0] neg_hi:[0,1]
	v_pk_add_f32 v[102:103], v[30:31], v[110:111] op_sel:[0,1] op_sel_hi:[1,0] neg_lo:[0,1]
	v_pk_add_f32 v[20:21], v[120:121], v[126:127]
	v_pk_add_f32 v[100:101], v[120:121], v[126:127] neg_lo:[0,1] neg_hi:[0,1]
	v_pk_add_f32 v[16:17], v[118:119], v[108:109] op_sel:[0,1] op_sel_hi:[1,0]
	v_pk_add_f32 v[98:99], v[118:119], v[108:109] op_sel:[0,1] op_sel_hi:[1,0] neg_lo:[0,1] neg_hi:[0,1]
	v_pk_add_f32 v[12:13], v[112:113], v[116:117]
	v_pk_add_f32 v[96:97], v[112:113], v[116:117] neg_lo:[0,1] neg_hi:[0,1]
	v_pk_add_f32 v[8:9], v[94:95], v[128:129] op_sel:[0,1] op_sel_hi:[1,0]
	v_pk_add_f32 v[94:95], v[94:95], v[128:129] op_sel:[0,1] op_sel_hi:[1,0] neg_lo:[0,1] neg_hi:[0,1]
	v_pk_add_f32 v[4:5], v[130:131], v[92:93]
	v_pk_add_f32 v[92:93], v[130:131], v[92:93] neg_lo:[0,1] neg_hi:[0,1]
	v_pk_add_f32 v[0:1], v[132:133], v[86:87] op_sel:[0,1] op_sel_hi:[1,0] neg_hi:[0,1]
	v_pk_add_f32 v[86:87], v[132:133], v[86:87] op_sel:[0,1] op_sel_hi:[1,0] neg_lo:[0,1]
	v_pk_add_f32 v[30:31], v[134:135], v[136:137]
	v_pk_add_f32 v[120:121], v[134:135], v[136:137] neg_lo:[0,1] neg_hi:[0,1]
	v_pk_add_f32 v[26:27], v[106:107], v[114:115] op_sel:[0,1] op_sel_hi:[1,0]
	v_pk_add_f32 v[118:119], v[106:107], v[114:115] op_sel:[0,1] op_sel_hi:[1,0] neg_lo:[0,1] neg_hi:[0,1]
	v_pk_add_f32 v[22:23], v[138:139], v[18:19]
	v_pk_add_f32 v[116:117], v[138:139], v[18:19] neg_lo:[0,1] neg_hi:[0,1]
	v_pk_add_f32 v[18:19], v[140:141], v[142:143] op_sel:[0,1] op_sel_hi:[1,0]
	v_pk_add_f32 v[114:115], v[140:141], v[142:143] op_sel:[0,1] op_sel_hi:[1,0] neg_lo:[0,1] neg_hi:[0,1]
	v_pk_add_f32 v[14:15], v[144:145], v[10:11]
	v_pk_add_f32 v[112:113], v[144:145], v[10:11] neg_lo:[0,1] neg_hi:[0,1]
	v_pk_add_f32 v[10:11], v[158:159], v[160:161] op_sel:[0,1] op_sel_hi:[1,0]
	v_pk_add_f32 v[110:111], v[158:159], v[160:161] op_sel:[0,1] op_sel_hi:[1,0] neg_lo:[0,1] neg_hi:[0,1]
	v_pk_add_f32 v[6:7], v[162:163], v[166:167]
	v_pk_add_f32 v[108:109], v[162:163], v[166:167] neg_lo:[0,1] neg_hi:[0,1]
	v_pk_add_f32 v[2:3], v[164:165], v[168:169] op_sel:[0,1] op_sel_hi:[1,0]
	v_pk_add_f32 v[106:107], v[164:165], v[168:169] op_sel:[0,1] op_sel_hi:[1,0] neg_lo:[0,1] neg_hi:[0,1]

.LBB0_670:
	v_add_u32_e32 v160, 0x11000, v155
	v_lshlrev_b32_e32 v161, 3, v154
	v_add_u32_e32 v161, 0x2200, v161
	v_add_u32_e32 v162, 0x11100, v156
	v_cmp_ne_u32_e32 vcc, 0, v32
	v_cndmask_b32_e32 v163, 0, v154, vcc
	v_lshlrev_b32_e32 v163, 3, v163
	v_add_u32_e32 v163, 0x11000, v163
	ds_read_b64 v[214:215], v160 offset:0
	ds_read_b64 v[216:217], v163
	ds_read_b64 v[218:219], v155 offset:0
	ds_read_b64 v[220:221], v160 offset:4352
	ds_read_b64 v[222:223], v162 offset:60928
	ds_read_b64 v[224:225], v155 offset:4352
	ds_read_b64 v[226:227], v160 offset:8704
	ds_read_b64 v[228:229], v161 offset:52224
	ds_read_b64 v[230:231], v155 offset:8704
	ds_read_b64 v[232:233], v160 offset:13056
	ds_read_b64 v[234:235], v162 offset:52224
	ds_read_b64 v[236:237], v155 offset:13056
	s_waitcnt lgkmcnt(9)
	v_add_f32_e32 v164, v215, v217
	v_sub_f32_e32 v165, v214, v216
	v_mul_f32_e32 v216, 0.5, v164
	v_mul_f32_e32 v214, -0.5, v165
	v_pk_mul_f32 v[214:215], v[218:219], v[214:215] op_sel:[1,0] op_sel_hi:[0,0]
	v_pk_fma_f32 v[158:159], v[218:219], v[216:217], v[214:215] neg_lo:[0,0,1] neg_hi:[0,0,1]
	v_pk_fma_f32 v[216:217], v[218:219], v[216:217], v[214:215] op_sel_hi:[1,0,1]
	s_nop 0
	v_mov_b32_e32 v159, v217
	v_pk_mul_f32 v[218:219], v[158:159], s[24:25]
	ds_write_b64 v155, v[218:219] offset:0
	s_waitcnt lgkmcnt(7)
	v_add_f32_e32 v164, v221, v223
	v_sub_f32_e32 v165, v220, v222
	v_mul_f32_e32 v222, 0.5, v164
	v_mul_f32_e32 v220, -0.5, v165
	v_pk_mul_f32 v[220:221], v[224:225], v[220:221] op_sel:[1,0] op_sel_hi:[0,0]
	v_pk_fma_f32 v[158:159], v[224:225], v[222:223], v[220:221] neg_lo:[0,0,1] neg_hi:[0,0,1]
	v_pk_fma_f32 v[222:223], v[224:225], v[222:223], v[220:221] op_sel_hi:[1,0,1]
	s_nop 0
	v_mov_b32_e32 v159, v223
	v_pk_mul_f32 v[224:225], v[158:159], s[24:25]
	ds_write_b64 v155, v[224:225] offset:4352
	ds_read_b64 v[182:183], v160 offset:17408
	ds_read_b64 v[184:185], v161 offset:43520
	ds_read_b64 v[186:187], v155 offset:17408
	ds_read_b64 v[188:189], v160 offset:21760
	ds_read_b64 v[190:191], v162 offset:43520
	ds_read_b64 v[192:193], v155 offset:21760
	s_waitcnt lgkmcnt(11)
	v_add_f32_e32 v164, v227, v229
	v_sub_f32_e32 v165, v226, v228
	v_mul_f32_e32 v228, 0.5, v164
	v_mul_f32_e32 v226, -0.5, v165
	v_pk_mul_f32 v[226:227], v[230:231], v[226:227] op_sel:[1,0] op_sel_hi:[0,0]
	v_pk_fma_f32 v[158:159], v[230:231], v[228:229], v[226:227] neg_lo:[0,0,1] neg_hi:[0,0,1]
	v_pk_fma_f32 v[228:229], v[230:231], v[228:229], v[226:227] op_sel_hi:[1,0,1]
	s_nop 0
	v_mov_b32_e32 v159, v229
	v_pk_mul_f32 v[230:231], v[158:159], s[24:25]
	ds_write_b64 v155, v[230:231] offset:8704
	s_waitcnt lgkmcnt(9)
	v_add_f32_e32 v164, v233, v235
	v_sub_f32_e32 v165, v232, v234
	v_mul_f32_e32 v234, 0.5, v164
	v_mul_f32_e32 v232, -0.5, v165
	v_pk_mul_f32 v[232:233], v[236:237], v[232:233] op_sel:[1,0] op_sel_hi:[0,0]
	v_pk_fma_f32 v[158:159], v[236:237], v[234:235], v[232:233] neg_lo:[0,0,1] neg_hi:[0,0,1]
	v_pk_fma_f32 v[234:235], v[236:237], v[234:235], v[232:233] op_sel_hi:[1,0,1]
	s_nop 0
	v_mov_b32_e32 v159, v235
	v_pk_mul_f32 v[236:237], v[158:159], s[24:25]
	ds_write_b64 v155, v[236:237] offset:13056
	ds_read_b64 v[214:215], v160 offset:26112
	ds_read_b64 v[216:217], v161 offset:34816
	ds_read_b64 v[218:219], v155 offset:26112
	ds_read_b64 v[220:221], v160 offset:30464
	ds_read_b64 v[222:223], v162 offset:34816
	ds_read_b64 v[224:225], v155 offset:30464
	s_waitcnt lgkmcnt(11)
	v_add_f32_e32 v164, v183, v185
	v_sub_f32_e32 v165, v182, v184
	v_mul_f32_e32 v184, 0.5, v164
	v_mul_f32_e32 v182, -0.5, v165
	v_pk_mul_f32 v[182:183], v[186:187], v[182:183] op_sel:[1,0] op_sel_hi:[0,0]
	v_pk_fma_f32 v[158:159], v[186:187], v[184:185], v[182:183] neg_lo:[0,0,1] neg_hi:[0,0,1]
	v_pk_fma_f32 v[184:185], v[186:187], v[184:185], v[182:183] op_sel_hi:[1,0,1]
	s_nop 0
	v_mov_b32_e32 v159, v185
	v_pk_mul_f32 v[186:187], v[158:159], s[24:25]
	ds_write_b64 v155, v[186:187] offset:17408
	s_waitcnt lgkmcnt(9)
	v_add_f32_e32 v164, v189, v191
	v_sub_f32_e32 v165, v188, v190
	v_mul_f32_e32 v190, 0.5, v164
	v_mul_f32_e32 v188, -0.5, v165
	v_pk_mul_f32 v[188:189], v[192:193], v[188:189] op_sel:[1,0] op_sel_hi:[0,0]
	v_pk_fma_f32 v[158:159], v[192:193], v[190:191], v[188:189] neg_lo:[0,0,1] neg_hi:[0,0,1]
	v_pk_fma_f32 v[190:191], v[192:193], v[190:191], v[188:189] op_sel_hi:[1,0,1]
	s_nop 0
	v_mov_b32_e32 v159, v191
	v_pk_mul_f32 v[192:193], v[158:159], s[24:25]
	ds_write_b64 v155, v[192:193] offset:21760
	ds_read_b64 v[226:227], v160 offset:34816
	ds_read_b64 v[228:229], v161 offset:26112
	ds_read_b64 v[230:231], v155 offset:34816
	ds_read_b64 v[232:233], v160 offset:39168
	ds_read_b64 v[234:235], v162 offset:26112
	ds_read_b64 v[236:237], v155 offset:39168
	s_waitcnt lgkmcnt(11)
	v_add_f32_e32 v164, v215, v217
	v_sub_f32_e32 v165, v214, v216
	v_mul_f32_e32 v216, 0.5, v164
	v_mul_f32_e32 v214, -0.5, v165
	v_pk_mul_f32 v[214:215], v[218:219], v[214:215] op_sel:[1,0] op_sel_hi:[0,0]
	v_pk_fma_f32 v[158:159], v[218:219], v[216:217], v[214:215] neg_lo:[0,0,1] neg_hi:[0,0,1]
	v_pk_fma_f32 v[216:217], v[218:219], v[216:217], v[214:215] op_sel_hi:[1,0,1]
	s_nop 0
	v_mov_b32_e32 v159, v217
	v_pk_mul_f32 v[218:219], v[158:159], s[24:25]
	ds_write_b64 v155, v[218:219] offset:26112
	s_waitcnt lgkmcnt(9)
	v_add_f32_e32 v164, v221, v223
	v_sub_f32_e32 v165, v220, v222
	v_mul_f32_e32 v222, 0.5, v164
	v_mul_f32_e32 v220, -0.5, v165
	v_pk_mul_f32 v[220:221], v[224:225], v[220:221] op_sel:[1,0] op_sel_hi:[0,0]
	v_pk_fma_f32 v[158:159], v[224:225], v[222:223], v[220:221] neg_lo:[0,0,1] neg_hi:[0,0,1]
	v_pk_fma_f32 v[222:223], v[224:225], v[222:223], v[220:221] op_sel_hi:[1,0,1]
	s_nop 0
	v_mov_b32_e32 v159, v223
	v_pk_mul_f32 v[224:225], v[158:159], s[24:25]
	ds_write_b64 v155, v[224:225] offset:30464
	ds_read_b64 v[182:183], v160 offset:43520
	ds_read_b64 v[184:185], v161 offset:17408
	ds_read_b64 v[186:187], v155 offset:43520
	ds_read_b64 v[188:189], v160 offset:47872
	ds_read_b64 v[190:191], v162 offset:17408
	ds_read_b64 v[192:193], v155 offset:47872
	s_waitcnt lgkmcnt(11)
	v_add_f32_e32 v164, v227, v229
	v_sub_f32_e32 v165, v226, v228
	v_mul_f32_e32 v228, 0.5, v164
	v_mul_f32_e32 v226, -0.5, v165
	v_pk_mul_f32 v[226:227], v[230:231], v[226:227] op_sel:[1,0] op_sel_hi:[0,0]
	v_pk_fma_f32 v[158:159], v[230:231], v[228:229], v[226:227] neg_lo:[0,0,1] neg_hi:[0,0,1]
	v_pk_fma_f32 v[228:229], v[230:231], v[228:229], v[226:227] op_sel_hi:[1,0,1]
	s_nop 0
	v_mov_b32_e32 v159, v229
	v_pk_mul_f32 v[230:231], v[158:159], s[24:25]
	ds_write_b64 v155, v[230:231] offset:34816
	s_waitcnt lgkmcnt(9)
	v_add_f32_e32 v164, v233, v235
	v_sub_f32_e32 v165, v232, v234
	v_mul_f32_e32 v234, 0.5, v164
	v_mul_f32_e32 v232, -0.5, v165
	v_pk_mul_f32 v[232:233], v[236:237], v[232:233] op_sel:[1,0] op_sel_hi:[0,0]
	v_pk_fma_f32 v[158:159], v[236:237], v[234:235], v[232:233] neg_lo:[0,0,1] neg_hi:[0,0,1]
	v_pk_fma_f32 v[234:235], v[236:237], v[234:235], v[232:233] op_sel_hi:[1,0,1]
	s_nop 0
	v_mov_b32_e32 v159, v235
	v_pk_mul_f32 v[236:237], v[158:159], s[24:25]
	ds_write_b64 v155, v[236:237] offset:39168
	ds_read_b64 v[214:215], v160 offset:52224
	ds_read_b64 v[216:217], v161 offset:8704
	ds_read_b64 v[218:219], v155 offset:52224
	ds_read_b64 v[220:221], v160 offset:56576
	ds_read_b64 v[222:223], v162 offset:8704
	ds_read_b64 v[224:225], v155 offset:56576
	s_waitcnt lgkmcnt(11)
	v_add_f32_e32 v164, v183, v185
	v_sub_f32_e32 v165, v182, v184
	v_mul_f32_e32 v184, 0.5, v164
	v_mul_f32_e32 v182, -0.5, v165
	v_pk_mul_f32 v[182:183], v[186:187], v[182:183] op_sel:[1,0] op_sel_hi:[0,0]
	v_pk_fma_f32 v[158:159], v[186:187], v[184:185], v[182:183] neg_lo:[0,0,1] neg_hi:[0,0,1]
	v_pk_fma_f32 v[184:185], v[186:187], v[184:185], v[182:183] op_sel_hi:[1,0,1]
	s_nop 0
	v_mov_b32_e32 v159, v185
	v_pk_mul_f32 v[186:187], v[158:159], s[24:25]
	ds_write_b64 v155, v[186:187] offset:43520
	s_waitcnt lgkmcnt(9)
	v_add_f32_e32 v164, v189, v191
	v_sub_f32_e32 v165, v188, v190
	v_mul_f32_e32 v190, 0.5, v164
	v_mul_f32_e32 v188, -0.5, v165
	v_pk_mul_f32 v[188:189], v[192:193], v[188:189] op_sel:[1,0] op_sel_hi:[0,0]
	v_pk_fma_f32 v[158:159], v[192:193], v[190:191], v[188:189] neg_lo:[0,0,1] neg_hi:[0,0,1]
	v_pk_fma_f32 v[190:191], v[192:193], v[190:191], v[188:189] op_sel_hi:[1,0,1]
	s_nop 0
	v_mov_b32_e32 v159, v191
	v_pk_mul_f32 v[192:193], v[158:159], s[24:25]
	ds_write_b64 v155, v[192:193] offset:47872
	ds_read_b64 v[226:227], v160 offset:60928
	ds_read_b64 v[228:229], v161 offset:0
	ds_read_b64 v[230:231], v155 offset:60928
	ds_read_b64 v[232:233], v160 offset:65280
	ds_read_b64 v[234:235], v162 offset:0
	ds_read_b64 v[236:237], v155 offset:65280
	s_waitcnt lgkmcnt(11)
	v_add_f32_e32 v164, v215, v217
	v_sub_f32_e32 v165, v214, v216
	v_mul_f32_e32 v216, 0.5, v164
	v_mul_f32_e32 v214, -0.5, v165
	v_pk_mul_f32 v[214:215], v[218:219], v[214:215] op_sel:[1,0] op_sel_hi:[0,0]
	v_pk_fma_f32 v[158:159], v[218:219], v[216:217], v[214:215] neg_lo:[0,0,1] neg_hi:[0,0,1]
	v_pk_fma_f32 v[216:217], v[218:219], v[216:217], v[214:215] op_sel_hi:[1,0,1]
	s_nop 0
	v_mov_b32_e32 v159, v217
	v_pk_mul_f32 v[218:219], v[158:159], s[24:25]
	ds_write_b64 v155, v[218:219] offset:52224
	s_waitcnt lgkmcnt(9)
	v_add_f32_e32 v164, v221, v223
	v_sub_f32_e32 v165, v220, v222
	v_mul_f32_e32 v222, 0.5, v164
	v_mul_f32_e32 v220, -0.5, v165
	v_pk_mul_f32 v[220:221], v[224:225], v[220:221] op_sel:[1,0] op_sel_hi:[0,0]
	v_pk_fma_f32 v[158:159], v[224:225], v[222:223], v[220:221] neg_lo:[0,0,1] neg_hi:[0,0,1]
	v_pk_fma_f32 v[222:223], v[224:225], v[222:223], v[220:221] op_sel_hi:[1,0,1]
	s_nop 0
	v_mov_b32_e32 v159, v223
	v_pk_mul_f32 v[224:225], v[158:159], s[24:25]
	ds_write_b64 v155, v[224:225] offset:56576
	s_waitcnt lgkmcnt(5)
	v_add_f32_e32 v164, v227, v229
	v_sub_f32_e32 v165, v226, v228
	v_mul_f32_e32 v228, 0.5, v164
	v_mul_f32_e32 v226, -0.5, v165
	v_pk_mul_f32 v[226:227], v[230:231], v[226:227] op_sel:[1,0] op_sel_hi:[0,0]
	v_pk_fma_f32 v[158:159], v[230:231], v[228:229], v[226:227] neg_lo:[0,0,1] neg_hi:[0,0,1]
	v_pk_fma_f32 v[228:229], v[230:231], v[228:229], v[226:227] op_sel_hi:[1,0,1]
	s_nop 0
	v_mov_b32_e32 v159, v229
	v_pk_mul_f32 v[230:231], v[158:159], s[24:25]
	ds_write_b64 v155, v[230:231] offset:60928
	s_waitcnt lgkmcnt(3)
	v_add_f32_e32 v164, v233, v235
	v_sub_f32_e32 v165, v232, v234
	v_mul_f32_e32 v234, 0.5, v164
	v_mul_f32_e32 v232, -0.5, v165
	v_pk_mul_f32 v[232:233], v[236:237], v[232:233] op_sel:[1,0] op_sel_hi:[0,0]
	v_pk_fma_f32 v[158:159], v[236:237], v[234:235], v[232:233] neg_lo:[0,0,1] neg_hi:[0,0,1]
	v_pk_fma_f32 v[234:235], v[236:237], v[234:235], v[232:233] op_sel_hi:[1,0,1]
	s_nop 0
	v_mov_b32_e32 v159, v235
	v_pk_mul_f32 v[236:237], v[158:159], s[24:25]
	ds_write_b64 v155, v[236:237] offset:65280
	s_mov_b32 s4, 16
	s_cmp_lg_u32 s4, 16
	s_waitcnt lgkmcnt(0)
	s_barrier
	s_and_saveexec_b64 s[28:29], s[40:41]
	s_cbranch_execz .LBB0_673
	ds_read_b64 v[0:1], v153
	ds_read_b64 v[2:3], v153 offset:2176
	ds_read_b64 v[4:5], v153 offset:4352
	ds_read_b64 v[6:7], v153 offset:6528
	ds_read_b64 v[8:9], v153 offset:8704
	ds_read_b64 v[10:11], v153 offset:10880
	ds_read_b64 v[12:13], v153 offset:13056
	ds_read_b64 v[14:15], v153 offset:15232
	ds_read_b64 v[16:17], v153 offset:17408
	ds_read_b64 v[18:19], v153 offset:19584
	ds_read_b64 v[20:21], v153 offset:21760
	ds_read_b64 v[22:23], v153 offset:23936
	ds_read_b64 v[24:25], v153 offset:26112
	ds_read_b64 v[26:27], v153 offset:28288
	ds_read_b64 v[28:29], v153 offset:30464
	ds_read_b64 v[30:31], v153 offset:32640
	ds_read_b64 v[58:59], v153 offset:34816
	ds_read_b64 v[60:61], v153 offset:41344
	ds_read_b64 v[94:95], v153 offset:43520
	ds_read_b64 v[96:97], v153 offset:45696
	ds_read_b64 v[98:99], v153 offset:47872
	ds_read_b64 v[100:101], v153 offset:50048
	ds_read_b64 v[102:103], v153 offset:52224
	ds_read_b64 v[104:105], v153 offset:54400
	ds_read_b64 v[106:107], v153 offset:56576
	ds_read_b64 v[108:109], v153 offset:58752
	ds_read_b64 v[110:111], v153 offset:60928
	ds_read_b64 v[112:113], v153 offset:63104
	ds_read_b64 v[114:115], v153 offset:65280
	ds_read_b64 v[116:117], v153 offset:36992
	ds_read_b64 v[118:119], v153 offset:39168
	ds_read_b64 v[120:121], v33
	s_waitcnt lgkmcnt(14)
	v_pk_add_f32 v[124:125], v[0:1], v[58:59]
	v_pk_add_f32 v[0:1], v[0:1], v[58:59] neg_lo:[0,1] neg_hi:[0,1]
	s_waitcnt lgkmcnt(2)
	v_pk_add_f32 v[58:59], v[2:3], v[116:117]
	v_pk_add_f32 v[2:3], v[2:3], v[116:117] neg_lo:[0,1] neg_hi:[0,1]
	s_mov_b32 s11, s14
	v_pk_mul_f32 v[116:117], v[2:3], s[16:17]
	s_mov_b32 s13, s86
	v_pk_fma_f32 v[2:3], v[2:3], s[6:7], v[116:117] op_sel:[0,0,1] op_sel_hi:[1,0,0]
	s_waitcnt lgkmcnt(1)
	v_pk_add_f32 v[116:117], v[4:5], v[118:119]
	v_pk_add_f32 v[4:5], v[4:5], v[118:119] neg_lo:[0,1] neg_hi:[0,1]
	s_mov_b32 s4, s21
	v_pk_mul_f32 v[118:119], v[4:5], s[18:19]
	s_mov_b32 s35, s30
	v_pk_fma_f32 v[4:5], v[4:5], s[30:31], v[118:119] op_sel:[0,0,1] op_sel_hi:[1,0,0]
	v_pk_add_f32 v[118:119], v[6:7], v[60:61]
	v_pk_add_f32 v[6:7], v[6:7], v[60:61] neg_lo:[0,1] neg_hi:[0,1]
	s_mov_b32 s8, s19
	v_pk_mul_f32 v[60:61], v[6:7], s[20:21]
	s_mov_b32 s77, s6
	v_pk_fma_f32 v[6:7], v[6:7], s[86:87], v[60:61] op_sel:[0,0,1] op_sel_hi:[1,0,0]
	v_pk_add_f32 v[60:61], v[8:9], v[94:95]
	v_pk_add_f32 v[8:9], v[8:9], v[94:95] neg_lo:[0,1] neg_hi:[0,1]
	s_mov_b32 s26, s17
	v_pk_mul_f32 v[94:95], v[8:9], s[10:11]
	s_nop 0
	v_pk_fma_f32 v[8:9], v[8:9], s[14:15], v[94:95] op_sel:[0,0,1] op_sel_hi:[1,0,0]
	v_pk_add_f32 v[94:95], v[10:11], v[96:97]
	v_pk_add_f32 v[10:11], v[10:11], v[96:97] neg_lo:[0,1] neg_hi:[0,1]
	s_nop 0
	v_pk_mul_f32 v[96:97], v[10:11], s[12:13]
	s_nop 0
	v_pk_fma_f32 v[10:11], v[10:11], s[4:5], v[96:97] op_sel:[0,0,1] op_sel_hi:[1,0,0]
	v_pk_add_f32 v[96:97], v[12:13], v[98:99]
	v_pk_add_f32 v[12:13], v[12:13], v[98:99] neg_lo:[0,1] neg_hi:[0,1]
	s_nop 0
	v_pk_mul_f32 v[98:99], v[12:13], s[34:35]
	s_nop 0
	v_pk_fma_f32 v[12:13], v[12:13], s[8:9], v[98:99] op_sel:[0,0,1] op_sel_hi:[1,0,0]
	v_pk_add_f32 v[98:99], v[14:15], v[100:101]
	v_pk_add_f32 v[14:15], v[14:15], v[100:101] neg_lo:[0,1] neg_hi:[0,1]
	s_nop 0
	v_pk_mul_f32 v[100:101], v[14:15], s[76:77]
	s_nop 0
	v_pk_fma_f32 v[14:15], v[14:15], s[26:27], v[100:101] op_sel:[0,0,1] op_sel_hi:[1,0,0]
	v_pk_add_f32 v[100:101], v[16:17], v[102:103]
	v_pk_add_f32 v[16:17], v[16:17], v[102:103] neg_lo:[0,1] neg_hi:[0,1]
	v_pk_add_f32 v[102:103], v[18:19], v[104:105]
	v_pk_add_f32 v[18:19], v[18:19], v[104:105] neg_lo:[0,1] neg_hi:[0,1]
	s_nop 0
	v_pk_mul_f32 v[104:105], v[18:19], s[76:77]
	s_nop 0
	v_pk_fma_f32 v[18:19], v[18:19], s[26:27], v[104:105] op_sel:[0,0,1] op_sel_hi:[1,0,0] neg_lo:[1,0,0] neg_hi:[1,0,0]
	v_pk_add_f32 v[104:105], v[20:21], v[106:107]
	v_pk_add_f32 v[20:21], v[20:21], v[106:107] neg_lo:[0,1] neg_hi:[0,1]
	s_nop 0
	v_pk_mul_f32 v[106:107], v[20:21], s[34:35]
	s_nop 0
	v_pk_fma_f32 v[20:21], v[20:21], s[8:9], v[106:107] op_sel:[0,0,1] op_sel_hi:[1,0,0] neg_lo:[1,0,0] neg_hi:[1,0,0]
	v_pk_add_f32 v[106:107], v[22:23], v[108:109]
	v_pk_add_f32 v[22:23], v[22:23], v[108:109] neg_lo:[0,1] neg_hi:[0,1]
	s_nop 0
	v_pk_mul_f32 v[108:109], v[22:23], s[12:13]
	s_nop 0
	v_pk_fma_f32 v[22:23], v[22:23], s[4:5], v[108:109] op_sel:[0,0,1] op_sel_hi:[1,0,0] neg_lo:[1,0,0] neg_hi:[1,0,0]
	v_pk_add_f32 v[108:109], v[24:25], v[110:111]
	v_pk_add_f32 v[24:25], v[24:25], v[110:111] neg_lo:[0,1] neg_hi:[0,1]
	s_nop 0
	v_pk_mul_f32 v[110:111], v[24:25], s[10:11]
	s_nop 0
	v_pk_fma_f32 v[24:25], v[24:25], s[14:15], v[110:111] op_sel:[0,0,1] op_sel_hi:[1,0,0] neg_lo:[1,0,0] neg_hi:[1,0,0]
	v_pk_add_f32 v[110:111], v[26:27], v[112:113]
	v_pk_add_f32 v[26:27], v[26:27], v[112:113] neg_lo:[0,1] neg_hi:[0,1]
	s_nop 0
	v_pk_mul_f32 v[112:113], v[26:27], s[20:21]
	s_nop 0
	v_pk_fma_f32 v[26:27], v[26:27], s[86:87], v[112:113] op_sel:[0,0,1] op_sel_hi:[1,0,0] neg_lo:[1,0,0] neg_hi:[1,0,0]
	v_pk_add_f32 v[112:113], v[28:29], v[114:115]
	v_pk_add_f32 v[28:29], v[28:29], v[114:115] neg_lo:[0,1] neg_hi:[0,1]
	s_nop 0
	v_pk_mul_f32 v[114:115], v[28:29], s[18:19]
	s_nop 0
	v_pk_fma_f32 v[28:29], v[28:29], s[30:31], v[114:115] op_sel:[0,0,1] op_sel_hi:[1,0,0] neg_lo:[1,0,0] neg_hi:[1,0,0]
	s_waitcnt lgkmcnt(0)
	v_pk_add_f32 v[114:115], v[30:31], v[120:121]
	v_pk_add_f32 v[30:31], v[30:31], v[120:121] neg_lo:[0,1] neg_hi:[0,1]
	s_nop 0
	v_pk_mul_f32 v[120:121], v[30:31], s[16:17]
	s_nop 0
	v_pk_fma_f32 v[30:31], v[30:31], s[6:7], v[120:121] op_sel:[0,0,1] op_sel_hi:[1,0,0] neg_lo:[1,0,0] neg_hi:[1,0,0]
	v_pk_add_f32 v[120:121], v[124:125], v[100:101]
	v_pk_add_f32 v[100:101], v[124:125], v[100:101] neg_lo:[0,1] neg_hi:[0,1]
	v_pk_add_f32 v[124:125], v[58:59], v[102:103]
	v_pk_add_f32 v[58:59], v[58:59], v[102:103] neg_lo:[0,1] neg_hi:[0,1]
	s_nop 0
	v_pk_mul_f32 v[102:103], v[58:59], s[18:19]
	s_nop 0
	v_pk_fma_f32 v[58:59], v[58:59], s[30:31], v[102:103] op_sel:[0,0,1] op_sel_hi:[1,0,0]
	v_pk_add_f32 v[102:103], v[116:117], v[104:105]
	v_pk_add_f32 v[104:105], v[116:117], v[104:105] neg_lo:[0,1] neg_hi:[0,1]
	s_nop 0
	v_pk_mul_f32 v[116:117], v[104:105], s[10:11]
	s_nop 0
	v_pk_fma_f32 v[104:105], v[104:105], s[14:15], v[116:117] op_sel:[0,0,1] op_sel_hi:[1,0,0]
	v_pk_add_f32 v[116:117], v[118:119], v[106:107]
	v_pk_add_f32 v[106:107], v[118:119], v[106:107] neg_lo:[0,1] neg_hi:[0,1]
	s_nop 0
	v_pk_mul_f32 v[118:119], v[106:107], s[34:35]
	s_nop 0
	v_pk_fma_f32 v[106:107], v[106:107], s[8:9], v[118:119] op_sel:[0,0,1] op_sel_hi:[1,0,0]
	v_pk_add_f32 v[118:119], v[60:61], v[108:109]
	v_pk_add_f32 v[60:61], v[60:61], v[108:109] neg_lo:[0,1] neg_hi:[0,1]
	v_pk_add_f32 v[108:109], v[94:95], v[110:111]
	v_pk_add_f32 v[94:95], v[94:95], v[110:111] neg_lo:[0,1] neg_hi:[0,1]
	s_nop 0
	v_pk_mul_f32 v[110:111], v[94:95], s[34:35]
	s_nop 0
	v_pk_fma_f32 v[94:95], v[94:95], s[8:9], v[110:111] op_sel:[0,0,1] op_sel_hi:[1,0,0] neg_lo:[1,0,0] neg_hi:[1,0,0]
	v_pk_add_f32 v[110:111], v[96:97], v[112:113]
	v_pk_add_f32 v[96:97], v[96:97], v[112:113] neg_lo:[0,1] neg_hi:[0,1]
	s_nop 0
	v_pk_mul_f32 v[112:113], v[96:97], s[10:11]
	s_nop 0
	v_pk_fma_f32 v[96:97], v[96:97], s[14:15], v[112:113] op_sel:[0,0,1] op_sel_hi:[1,0,0] neg_lo:[1,0,0] neg_hi:[1,0,0]
	v_pk_add_f32 v[112:113], v[98:99], v[114:115]
	v_pk_add_f32 v[98:99], v[98:99], v[114:115] neg_lo:[0,1] neg_hi:[0,1]
	s_nop 0
	v_pk_mul_f32 v[114:115], v[98:99], s[18:19]
	s_nop 0
	v_pk_fma_f32 v[98:99], v[98:99], s[30:31], v[114:115] op_sel:[0,0,1] op_sel_hi:[1,0,0] neg_lo:[1,0,0] neg_hi:[1,0,0]
	v_pk_add_f32 v[114:115], v[0:1], v[16:17] op_sel:[0,1] op_sel_hi:[1,0] neg_hi:[0,1]
	v_pk_add_f32 v[0:1], v[0:1], v[16:17] op_sel:[0,1] op_sel_hi:[1,0] neg_lo:[0,1]
	v_pk_add_f32 v[16:17], v[2:3], v[18:19]
	v_pk_add_f32 v[2:3], v[2:3], v[18:19] neg_lo:[0,1] neg_hi:[0,1]
	s_nop 0
	v_pk_mul_f32 v[18:19], v[2:3], s[18:19]
	s_nop 0
	v_pk_fma_f32 v[2:3], v[2:3], s[30:31], v[18:19] op_sel:[0,0,1] op_sel_hi:[1,0,0]
	v_pk_add_f32 v[18:19], v[4:5], v[20:21]
	v_pk_add_f32 v[4:5], v[4:5], v[20:21] neg_lo:[0,1] neg_hi:[0,1]
	s_nop 0
	v_pk_mul_f32 v[20:21], v[4:5], s[10:11]
	s_nop 0
	v_pk_fma_f32 v[4:5], v[4:5], s[14:15], v[20:21] op_sel:[0,0,1] op_sel_hi:[1,0,0]
	v_pk_add_f32 v[20:21], v[6:7], v[22:23]
	v_pk_add_f32 v[6:7], v[6:7], v[22:23] neg_lo:[0,1] neg_hi:[0,1]
	s_nop 0
	v_pk_mul_f32 v[22:23], v[6:7], s[34:35]
	s_nop 0
	v_pk_fma_f32 v[6:7], v[6:7], s[8:9], v[22:23] op_sel:[0,0,1] op_sel_hi:[1,0,0]
	v_pk_add_f32 v[22:23], v[8:9], v[24:25]
	v_pk_add_f32 v[8:9], v[8:9], v[24:25] neg_lo:[0,1] neg_hi:[0,1]
	v_pk_add_f32 v[24:25], v[10:11], v[26:27]
	v_pk_add_f32 v[10:11], v[10:11], v[26:27] neg_lo:[0,1] neg_hi:[0,1]
	s_nop 0
	v_pk_mul_f32 v[26:27], v[10:11], s[34:35]
	s_nop 0
	v_pk_fma_f32 v[10:11], v[10:11], s[8:9], v[26:27] op_sel:[0,0,1] op_sel_hi:[1,0,0] neg_lo:[1,0,0] neg_hi:[1,0,0]
	v_pk_add_f32 v[26:27], v[12:13], v[28:29]
	v_pk_add_f32 v[12:13], v[12:13], v[28:29] neg_lo:[0,1] neg_hi:[0,1]
	s_nop 0
	v_pk_mul_f32 v[28:29], v[12:13], s[10:11]
	s_nop 0
	v_pk_fma_f32 v[12:13], v[12:13], s[14:15], v[28:29] op_sel:[0,0,1] op_sel_hi:[1,0,0] neg_lo:[1,0,0] neg_hi:[1,0,0]
	v_pk_add_f32 v[28:29], v[14:15], v[30:31]
	v_pk_add_f32 v[14:15], v[14:15], v[30:31] neg_lo:[0,1] neg_hi:[0,1]
	s_nop 0
	v_pk_mul_f32 v[30:31], v[14:15], s[18:19]
	s_nop 0
	v_pk_fma_f32 v[14:15], v[14:15], s[30:31], v[30:31] op_sel:[0,0,1] op_sel_hi:[1,0,0] neg_lo:[1,0,0] neg_hi:[1,0,0]
	v_pk_add_f32 v[30:31], v[120:121], v[118:119]
	v_pk_add_f32 v[118:119], v[120:121], v[118:119] neg_lo:[0,1] neg_hi:[0,1]
	v_pk_add_f32 v[120:121], v[124:125], v[108:109]
	v_pk_add_f32 v[108:109], v[124:125], v[108:109] neg_lo:[0,1] neg_hi:[0,1]
	s_nop 0
	v_pk_mul_f32 v[124:125], v[108:109], s[10:11]
	s_nop 0
	v_pk_fma_f32 v[108:109], v[108:109], s[14:15], v[124:125] op_sel:[0,0,1] op_sel_hi:[1,0,0]
	v_pk_add_f32 v[124:125], v[102:103], v[110:111]
	v_pk_add_f32 v[102:103], v[102:103], v[110:111] neg_lo:[0,1] neg_hi:[0,1]
	v_pk_add_f32 v[110:111], v[116:117], v[112:113]
	v_pk_add_f32 v[112:113], v[116:117], v[112:113] neg_lo:[0,1] neg_hi:[0,1]
	s_nop 0
	v_pk_mul_f32 v[116:117], v[112:113], s[10:11]
	s_nop 0
	v_pk_fma_f32 v[112:113], v[112:113], s[14:15], v[116:117] op_sel:[0,0,1] op_sel_hi:[1,0,0] neg_lo:[1,0,0] neg_hi:[1,0,0]
	v_pk_add_f32 v[116:117], v[100:101], v[60:61] op_sel:[0,1] op_sel_hi:[1,0] neg_hi:[0,1]
	v_pk_add_f32 v[60:61], v[100:101], v[60:61] op_sel:[0,1] op_sel_hi:[1,0] neg_lo:[0,1]
	v_pk_add_f32 v[100:101], v[58:59], v[94:95]
	v_pk_add_f32 v[58:59], v[58:59], v[94:95] neg_lo:[0,1] neg_hi:[0,1]
	v_pk_add_f32 v[126:127], v[108:109], v[112:113]
	v_pk_mul_f32 v[94:95], v[58:59], s[10:11]
	s_nop 0
	v_pk_fma_f32 v[58:59], v[58:59], s[14:15], v[94:95] op_sel:[0,0,1] op_sel_hi:[1,0,0]
	v_pk_add_f32 v[94:95], v[104:105], v[96:97]
	v_pk_add_f32 v[96:97], v[104:105], v[96:97] neg_lo:[0,1] neg_hi:[0,1]
	v_pk_add_f32 v[104:105], v[106:107], v[98:99]
	v_pk_add_f32 v[98:99], v[106:107], v[98:99] neg_lo:[0,1] neg_hi:[0,1]
	s_nop 0
	v_pk_mul_f32 v[106:107], v[98:99], s[10:11]
	v_pk_add_f32 v[130:131], v[60:61], v[96:97] op_sel:[0,1] op_sel_hi:[1,0] neg_hi:[0,1]
	v_pk_fma_f32 v[98:99], v[98:99], s[14:15], v[106:107] op_sel:[0,0,1] op_sel_hi:[1,0,0] neg_lo:[1,0,0] neg_hi:[1,0,0]
	v_pk_add_f32 v[106:107], v[114:115], v[22:23]
	v_pk_add_f32 v[22:23], v[114:115], v[22:23] neg_lo:[0,1] neg_hi:[0,1]
	v_pk_add_f32 v[114:115], v[16:17], v[24:25]
	v_pk_add_f32 v[16:17], v[16:17], v[24:25] neg_lo:[0,1] neg_hi:[0,1]
	v_pk_add_f32 v[132:133], v[60:61], v[96:97] op_sel:[0,1] op_sel_hi:[1,0] neg_lo:[0,1]
	v_pk_mul_f32 v[24:25], v[16:17], s[10:11]
	v_pk_add_f32 v[60:61], v[58:59], v[98:99]
	v_pk_fma_f32 v[16:17], v[16:17], s[14:15], v[24:25] op_sel:[0,0,1] op_sel_hi:[1,0,0]
	v_pk_add_f32 v[24:25], v[18:19], v[26:27]
	v_pk_add_f32 v[18:19], v[18:19], v[26:27] neg_lo:[0,1] neg_hi:[0,1]
	v_pk_add_f32 v[26:27], v[20:21], v[28:29]
	v_pk_add_f32 v[20:21], v[20:21], v[28:29] neg_lo:[0,1] neg_hi:[0,1]
	s_nop 0
	v_pk_mul_f32 v[28:29], v[20:21], s[10:11]
	v_pk_add_f32 v[58:59], v[58:59], v[98:99] neg_lo:[0,1] neg_hi:[0,1]
	v_pk_fma_f32 v[20:21], v[20:21], s[14:15], v[28:29] op_sel:[0,0,1] op_sel_hi:[1,0,0] neg_lo:[1,0,0] neg_hi:[1,0,0]
	v_pk_add_f32 v[28:29], v[0:1], v[8:9] op_sel:[0,1] op_sel_hi:[1,0] neg_hi:[0,1]
	v_pk_add_f32 v[0:1], v[0:1], v[8:9] op_sel:[0,1] op_sel_hi:[1,0] neg_lo:[0,1]
	v_pk_add_f32 v[8:9], v[2:3], v[10:11]
	v_pk_add_f32 v[2:3], v[2:3], v[10:11] neg_lo:[0,1] neg_hi:[0,1]
	v_pk_add_f32 v[134:135], v[106:107], v[24:25]
	v_pk_mul_f32 v[10:11], v[2:3], s[10:11]
	v_pk_add_f32 v[106:107], v[106:107], v[24:25] neg_lo:[0,1] neg_hi:[0,1]
	v_pk_fma_f32 v[2:3], v[2:3], s[14:15], v[10:11] op_sel:[0,0,1] op_sel_hi:[1,0,0]
	v_pk_add_f32 v[10:11], v[4:5], v[12:13]
	v_pk_add_f32 v[4:5], v[4:5], v[12:13] neg_lo:[0,1] neg_hi:[0,1]
	v_pk_add_f32 v[12:13], v[6:7], v[14:15]
	v_pk_add_f32 v[6:7], v[6:7], v[14:15] neg_lo:[0,1] neg_hi:[0,1]
	s_nop 0
	v_pk_mul_f32 v[14:15], v[6:7], s[10:11]
	v_pk_add_f32 v[24:25], v[114:115], v[26:27] neg_lo:[0,1] neg_hi:[0,1]
	v_pk_fma_f32 v[6:7], v[6:7], s[14:15], v[14:15] op_sel:[0,0,1] op_sel_hi:[1,0,0] neg_lo:[1,0,0] neg_hi:[1,0,0]
	v_pk_add_f32 v[14:15], v[30:31], v[124:125]
	v_pk_add_f32 v[30:31], v[30:31], v[124:125] neg_lo:[0,1] neg_hi:[0,1]
	v_pk_add_f32 v[124:125], v[120:121], v[110:111]
	v_pk_add_f32 v[110:111], v[120:121], v[110:111] neg_lo:[0,1] neg_hi:[0,1]
	v_pk_add_f32 v[120:121], v[118:119], v[102:103] op_sel:[0,1] op_sel_hi:[1,0] neg_hi:[0,1]
	v_pk_add_f32 v[118:119], v[118:119], v[102:103] op_sel:[0,1] op_sel_hi:[1,0] neg_lo:[0,1]
	v_pk_add_f32 v[102:103], v[108:109], v[112:113] neg_lo:[0,1] neg_hi:[0,1]
	v_pk_add_f32 v[112:113], v[116:117], v[94:95]
	v_pk_add_f32 v[94:95], v[116:117], v[94:95] neg_lo:[0,1] neg_hi:[0,1]
	v_pk_add_f32 v[116:117], v[100:101], v[104:105]
	v_pk_add_f32 v[100:101], v[100:101], v[104:105] neg_lo:[0,1] neg_hi:[0,1]
	v_pk_add_f32 v[138:139], v[22:23], v[18:19] op_sel:[0,1] op_sel_hi:[1,0] neg_hi:[0,1]
	v_pk_add_f32 v[140:141], v[22:23], v[18:19] op_sel:[0,1] op_sel_hi:[1,0] neg_lo:[0,1]
	v_pk_add_f32 v[18:19], v[16:17], v[20:21]
	v_pk_add_f32 v[16:17], v[16:17], v[20:21] neg_lo:[0,1] neg_hi:[0,1]
	v_pk_add_f32 v[144:145], v[28:29], v[10:11]
	v_pk_add_f32 v[158:159], v[28:29], v[10:11] neg_lo:[0,1] neg_hi:[0,1]
	v_pk_add_f32 v[10:11], v[8:9], v[12:13]
	v_pk_add_f32 v[8:9], v[8:9], v[12:13] neg_lo:[0,1] neg_hi:[0,1]
	v_pk_add_f32 v[162:163], v[0:1], v[4:5] op_sel:[0,1] op_sel_hi:[1,0] neg_hi:[0,1]
	v_pk_add_f32 v[164:165], v[0:1], v[4:5] op_sel:[0,1] op_sel_hi:[1,0] neg_lo:[0,1]
	v_pk_add_f32 v[0:1], v[2:3], v[6:7] neg_lo:[0,1] neg_hi:[0,1]
	v_pk_mul_f32 v[108:109], v[102:103], s[22:23]
	v_pk_mul_f32 v[128:129], v[100:101], s[22:23]
	v_pk_add_f32 v[136:137], v[114:115], v[26:27]
	v_pk_mul_f32 v[114:115], v[24:25], s[22:23]
	v_pk_mul_f32 v[142:143], v[16:17], s[22:23]
	v_pk_mul_f32 v[160:161], v[8:9], s[22:23]
	v_pk_add_f32 v[166:167], v[2:3], v[6:7]
	v_pk_mul_f32 v[168:169], v[0:1], s[22:23]
	v_pk_add_f32 v[28:29], v[14:15], v[124:125]
	v_pk_add_f32 v[104:105], v[14:15], v[124:125] neg_lo:[0,1] neg_hi:[0,1]
	v_pk_add_f32 v[24:25], v[30:31], v[110:111] op_sel:[0,1] op_sel_hi:[1,0] neg_hi:[0,1]
	v_pk_add_f32 v[102:103], v[30:31], v[110:111] op_sel:[0,1] op_sel_hi:[1,0] neg_lo:[0,1]
	v_pk_add_f32 v[20:21], v[120:121], v[126:127]
	v_pk_add_f32 v[100:101], v[120:121], v[126:127] neg_lo:[0,1] neg_hi:[0,1]
	v_pk_add_f32 v[16:17], v[118:119], v[108:109] op_sel:[0,1] op_sel_hi:[1,0]
	v_pk_add_f32 v[98:99], v[118:119], v[108:109] op_sel:[0,1] op_sel_hi:[1,0] neg_lo:[0,1] neg_hi:[0,1]
	v_pk_add_f32 v[12:13], v[112:113], v[116:117]
	v_pk_add_f32 v[96:97], v[112:113], v[116:117] neg_lo:[0,1] neg_hi:[0,1]
	v_pk_add_f32 v[8:9], v[94:95], v[128:129] op_sel:[0,1] op_sel_hi:[1,0]
	v_pk_add_f32 v[94:95], v[94:95], v[128:129] op_sel:[0,1] op_sel_hi:[1,0] neg_lo:[0,1] neg_hi:[0,1]
	v_pk_add_f32 v[4:5], v[130:131], v[60:61]
	v_pk_add_f32 v[60:61], v[130:131], v[60:61] neg_lo:[0,1] neg_hi:[0,1]
	v_pk_add_f32 v[0:1], v[132:133], v[58:59] op_sel:[0,1] op_sel_hi:[1,0] neg_hi:[0,1]
	v_pk_add_f32 v[58:59], v[132:133], v[58:59] op_sel:[0,1] op_sel_hi:[1,0] neg_lo:[0,1]
	v_pk_add_f32 v[30:31], v[134:135], v[136:137]
	v_pk_add_f32 v[120:121], v[134:135], v[136:137] neg_lo:[0,1] neg_hi:[0,1]
	v_pk_add_f32 v[26:27], v[106:107], v[114:115] op_sel:[0,1] op_sel_hi:[1,0]
	v_pk_add_f32 v[118:119], v[106:107], v[114:115] op_sel:[0,1] op_sel_hi:[1,0] neg_lo:[0,1] neg_hi:[0,1]
	v_pk_add_f32 v[22:23], v[138:139], v[18:19]
	v_pk_add_f32 v[116:117], v[138:139], v[18:19] neg_lo:[0,1] neg_hi:[0,1]
	v_pk_add_f32 v[18:19], v[140:141], v[142:143] op_sel:[0,1] op_sel_hi:[1,0]
	v_pk_add_f32 v[114:115], v[140:141], v[142:143] op_sel:[0,1] op_sel_hi:[1,0] neg_lo:[0,1] neg_hi:[0,1]
	v_pk_add_f32 v[14:15], v[144:145], v[10:11]
	v_pk_add_f32 v[112:113], v[144:145], v[10:11] neg_lo:[0,1] neg_hi:[0,1]
	v_pk_add_f32 v[10:11], v[158:159], v[160:161] op_sel:[0,1] op_sel_hi:[1,0]
	v_pk_add_f32 v[110:111], v[158:159], v[160:161] op_sel:[0,1] op_sel_hi:[1,0] neg_lo:[0,1] neg_hi:[0,1]
	v_pk_add_f32 v[6:7], v[162:163], v[166:167]
	v_pk_add_f32 v[108:109], v[162:163], v[166:167] neg_lo:[0,1] neg_hi:[0,1]
	v_pk_add_f32 v[2:3], v[164:165], v[168:169] op_sel:[0,1] op_sel_hi:[1,0]
	v_pk_add_f32 v[106:107], v[164:165], v[168:169] op_sel:[0,1] op_sel_hi:[1,0] neg_lo:[0,1] neg_hi:[0,1]
